# v10 with static priority: trailing (younger) wave half s_setprio 1 once per K-loop, all per-segment s_setprio removed in the six GEMM K-loops
# baseline (speedup 1.0000x reference)
.LBB0_179:
	s_add_u32 s67, s12, 0x100
	s_addc_u32 s43, s13, 0
	s_ashr_i32 s25, s24, 31
	s_lshl_b64 s[8:9], s[24:25], 20
	s_add_u32 s28, s15, s8
	s_addc_u32 s29, s17, s9
	s_and_b64 s[8:9], s[10:11], exec
	s_cselect_b32 s25, s29, s27
	s_cselect_b32 s36, s28, s26
	s_ashr_i32 s23, s22, 31
	s_lshl_b64 s[8:9], s[22:23], 20
	s_add_u32 s30, s1, s8
	s_addc_u32 s31, s3, s9
	s_and_b64 s[8:9], s[10:11], exec
	s_cselect_b32 s23, s31, s13
	s_cselect_b32 s37, s30, s12
	s_add_u32 s8, s26, 0x80080
	s_addc_u32 s9, s27, 0
	v_lshl_add_u64 v[132:133], s[8:9], 0, v[182:183]
	v_lshl_add_u64 v[134:135], s[8:9], 0, v[184:185]
	s_mov_b32 s42, -2
	s_mov_b64 s[8:9], 0
	s_and_b64 vcc, exec, s[20:21]
	s_cbranch_vccnz .Lsp_skip_180
	s_setprio 1
.Lsp_skip_180:
.LBB0_180:
	s_add_u32 s12, s26, s8
	s_addc_u32 s13, s27, s9
	s_add_u32 s12, s12, 0x100
	s_addc_u32 s13, s13, 0
	s_add_u32 s81, s67, s8
	s_addc_u32 s83, s43, s9
	s_add_i32 s95, 0, 0x10000
	s_cmpk_eq_i32 s8, 0xf00
	s_cselect_b32 s35, s25, s13
	s_cselect_b32 s34, s36, s12
	s_cselect_b32 s13, s23, s83
	s_cselect_b32 s12, s37, s81
	s_add_i32 s81, 0, 0x14000
	v_add_u32_e32 v148, s95, v230
	v_add_u32_e32 v164, s81, v230
	ds_read_b128 v[136:139], v148
	ds_read_b128 v[140:143], v148 offset:1024
	ds_read_b128 v[144:147], v148 offset:2048
	ds_read_b128 v[148:151], v148 offset:3072
	ds_read_b128 v[152:155], v164
	ds_read_b128 v[156:159], v164 offset:1024
	ds_read_b128 v[160:163], v164 offset:2048
	ds_read_b128 v[164:167], v164 offset:3072
	v_lshl_add_u64 v[196:197], v[132:133], 0, s[8:9]
	s_add_i32 m0, s39, 0xc000
	ds_read_b128 v[168:171], v242
	ds_read_b128 v[188:191], v242 offset:1024
	ds_read_b128 v[192:195], v242 offset:2048
	ds_read_b128 v[204:207], v242 offset:3072
	ds_read_b128 v[208:211], v242 offset:4096
	ds_read_b128 v[212:215], v242 offset:5120
	ds_read_b128 v[244:247], v242 offset:6144
	ds_read_b128 v[248:251], v242 offset:7168
	global_load_lds_dwordx4 v[196:197], off
	v_lshl_add_u64 v[196:197], v[134:135], 0, s[8:9]
	s_add_i32 m0, s39, 0xe000
	s_nop 0
	global_load_lds_dwordx4 v[196:197], off
	s_waitcnt vmcnt(8)
	s_waitcnt lgkmcnt(0)
	s_barrier
	v_mfma_f32_16x16x32_bf16 v[8:11], v[136:139], v[168:171], v[8:11]
	v_mfma_f32_16x16x32_bf16 v[128:131], v[144:147], v[168:171], v[128:131]
	v_mfma_f32_16x16x32_bf16 v[124:127], v[136:139], v[192:195], v[124:127]
	v_mfma_f32_16x16x32_bf16 v[120:123], v[144:147], v[192:195], v[120:123]
	v_mfma_f32_16x16x32_bf16 v[116:119], v[136:139], v[208:211], v[116:119]
	v_mfma_f32_16x16x32_bf16 v[112:115], v[144:147], v[208:211], v[112:115]
	v_mfma_f32_16x16x32_bf16 v[108:111], v[136:139], v[244:247], v[108:111]
	v_mfma_f32_16x16x32_bf16 v[104:107], v[144:147], v[244:247], v[104:107]
	v_mfma_f32_16x16x32_bf16 v[8:11], v[140:143], v[188:191], v[8:11]
	v_mfma_f32_16x16x32_bf16 v[128:131], v[148:151], v[188:191], v[128:131]
	v_mfma_f32_16x16x32_bf16 v[124:127], v[140:143], v[204:207], v[124:127]
	v_mfma_f32_16x16x32_bf16 v[120:123], v[148:151], v[204:207], v[120:123]
	v_mfma_f32_16x16x32_bf16 v[116:119], v[140:143], v[212:215], v[116:119]
	v_mfma_f32_16x16x32_bf16 v[112:115], v[148:151], v[212:215], v[112:115]
	v_mfma_f32_16x16x32_bf16 v[108:111], v[140:143], v[248:251], v[108:111]
	v_mfma_f32_16x16x32_bf16 v[104:107], v[148:151], v[248:251], v[104:107]
	v_mfma_f32_16x16x32_bf16 v[100:103], v[152:155], v[168:171], v[100:103]
	v_mfma_f32_16x16x32_bf16 v[96:99], v[160:163], v[168:171], v[96:99]
	v_mfma_f32_16x16x32_bf16 v[92:95], v[152:155], v[192:195], v[92:95]
	v_mfma_f32_16x16x32_bf16 v[88:91], v[160:163], v[192:195], v[88:91]
	v_mfma_f32_16x16x32_bf16 v[84:87], v[152:155], v[208:211], v[84:87]
	v_mfma_f32_16x16x32_bf16 v[80:83], v[160:163], v[208:211], v[80:83]
	v_mfma_f32_16x16x32_bf16 v[76:79], v[152:155], v[244:247], v[76:79]
	v_mfma_f32_16x16x32_bf16 v[72:75], v[160:163], v[244:247], v[72:75]
	v_mfma_f32_16x16x32_bf16 v[100:103], v[156:159], v[188:191], v[100:103]
	v_mfma_f32_16x16x32_bf16 v[96:99], v[164:167], v[188:191], v[96:99]
	v_mfma_f32_16x16x32_bf16 v[92:95], v[156:159], v[204:207], v[92:95]
	v_mfma_f32_16x16x32_bf16 v[88:91], v[164:167], v[204:207], v[88:91]
	v_mfma_f32_16x16x32_bf16 v[84:87], v[156:159], v[212:215], v[84:87]
	v_mfma_f32_16x16x32_bf16 v[80:83], v[164:167], v[212:215], v[80:83]
	v_mfma_f32_16x16x32_bf16 v[76:79], v[156:159], v[248:251], v[76:79]
	v_mfma_f32_16x16x32_bf16 v[72:75], v[164:167], v[248:251], v[72:75]
	s_barrier
	s_add_i32 s83, s95, s38
	v_lshl_add_u64 v[196:197], s[12:13], 0, v[172:173]
	s_mov_b32 m0, s83
	ds_read_b128 v[168:171], v242 offset:16384
	ds_read_b128 v[188:191], v242 offset:17408
	ds_read_b128 v[192:195], v242 offset:18432
	ds_read_b128 v[204:207], v242 offset:19456
	ds_read_b128 v[208:211], v242 offset:20480
	ds_read_b128 v[212:215], v242 offset:21504
	ds_read_b128 v[244:247], v242 offset:22528
	ds_read_b128 v[248:251], v242 offset:23552
	global_load_lds_dwordx4 v[196:197], off
	s_add_i32 m0, s83, 0x2000
	s_add_u32 vcc_lo, s12, 0x80000
	v_lshl_add_u64 v[198:199], s[12:13], 0, v[176:177]
	s_addc_u32 vcc_hi, s13, 0
	s_add_i32 s81, s81, s38
	global_load_lds_dwordx4 v[198:199], off
	v_lshl_add_u64 v[200:201], vcc, 0, v[172:173]
	s_mov_b32 m0, s81
	v_lshl_add_u64 v[202:203], s[34:35], 0, v[174:175]
	global_load_lds_dwordx4 v[200:201], off
	v_lshl_add_u64 v[200:201], vcc, 0, v[176:177]
	s_add_i32 m0, s81, 0x2000
	s_nop 0
	global_load_lds_dwordx4 v[200:201], off
	v_lshl_add_u64 v[200:201], s[34:35], 0, v[0:1]
	s_mov_b32 m0, s39
	s_nop 0
	global_load_lds_dwordx4 v[200:201], off
	s_mov_b32 m0, s46
	s_nop 0
	global_load_lds_dwordx4 v[202:203], off
	s_waitcnt vmcnt(8)
	s_waitcnt lgkmcnt(0)
	s_barrier
	v_mfma_f32_16x16x32_bf16 v[68:71], v[136:139], v[168:171], v[68:71]
	v_mfma_f32_16x16x32_bf16 v[64:67], v[144:147], v[168:171], v[64:67]
	v_mfma_f32_16x16x32_bf16 v[60:63], v[136:139], v[192:195], v[60:63]
	v_mfma_f32_16x16x32_bf16 v[56:59], v[144:147], v[192:195], v[56:59]
	v_mfma_f32_16x16x32_bf16 v[52:55], v[136:139], v[208:211], v[52:55]
	v_mfma_f32_16x16x32_bf16 v[48:51], v[144:147], v[208:211], v[48:51]
	v_mfma_f32_16x16x32_bf16 v[44:47], v[136:139], v[244:247], v[44:47]
	v_mfma_f32_16x16x32_bf16 v[40:43], v[144:147], v[244:247], v[40:43]
	v_mfma_f32_16x16x32_bf16 v[68:71], v[140:143], v[188:191], v[68:71]
	v_mfma_f32_16x16x32_bf16 v[64:67], v[148:151], v[188:191], v[64:67]
	v_mfma_f32_16x16x32_bf16 v[60:63], v[140:143], v[204:207], v[60:63]
	v_mfma_f32_16x16x32_bf16 v[56:59], v[148:151], v[204:207], v[56:59]
	v_mfma_f32_16x16x32_bf16 v[52:55], v[140:143], v[212:215], v[52:55]
	v_mfma_f32_16x16x32_bf16 v[48:51], v[148:151], v[212:215], v[48:51]
	v_mfma_f32_16x16x32_bf16 v[44:47], v[140:143], v[248:251], v[44:47]
	v_mfma_f32_16x16x32_bf16 v[40:43], v[148:151], v[248:251], v[40:43]
	v_mfma_f32_16x16x32_bf16 v[36:39], v[152:155], v[168:171], v[36:39]
	v_mfma_f32_16x16x32_bf16 v[32:35], v[160:163], v[168:171], v[32:35]
	v_mfma_f32_16x16x32_bf16 v[28:31], v[152:155], v[192:195], v[28:31]
	v_mfma_f32_16x16x32_bf16 v[24:27], v[160:163], v[192:195], v[24:27]
	v_mfma_f32_16x16x32_bf16 v[20:23], v[152:155], v[208:211], v[20:23]
	v_mfma_f32_16x16x32_bf16 v[16:19], v[160:163], v[208:211], v[16:19]
	v_mfma_f32_16x16x32_bf16 v[12:15], v[152:155], v[244:247], v[12:15]
	v_mfma_f32_16x16x32_bf16 v[4:7], v[160:163], v[244:247], v[4:7]
	v_mfma_f32_16x16x32_bf16 v[36:39], v[156:159], v[188:191], v[36:39]
	v_mfma_f32_16x16x32_bf16 v[32:35], v[164:167], v[188:191], v[32:35]
	v_mfma_f32_16x16x32_bf16 v[28:31], v[156:159], v[204:207], v[28:31]
	v_mfma_f32_16x16x32_bf16 v[24:27], v[164:167], v[204:207], v[24:27]
	v_mfma_f32_16x16x32_bf16 v[20:23], v[156:159], v[212:215], v[20:23]
	v_mfma_f32_16x16x32_bf16 v[16:19], v[164:167], v[212:215], v[16:19]
	v_mfma_f32_16x16x32_bf16 v[12:15], v[156:159], v[248:251], v[12:15]
	v_mfma_f32_16x16x32_bf16 v[4:7], v[164:167], v[248:251], v[4:7]
	s_barrier
	s_add_i32 s81, 0, 0x18000
	s_add_i32 s83, 0, 0x1c000
	v_add_u32_e32 v148, s81, v230
	v_add_u32_e32 v164, s83, v230
	ds_read_b128 v[136:139], v148
	ds_read_b128 v[140:143], v148 offset:1024
	ds_read_b128 v[144:147], v148 offset:2048
	ds_read_b128 v[148:151], v148 offset:3072
	ds_read_b128 v[152:155], v164
	ds_read_b128 v[156:159], v164 offset:1024
	ds_read_b128 v[160:163], v164 offset:2048
	ds_read_b128 v[164:167], v164 offset:3072
	s_add_u32 s34, s34, 0x80000
	s_addc_u32 s35, s35, 0
	s_mov_b32 m0, s47
	v_lshl_add_u64 v[216:217], s[34:35], 0, v[0:1]
	ds_read_b128 v[168:171], v242 offset:32768
	ds_read_b128 v[188:191], v242 offset:33792
	ds_read_b128 v[192:195], v242 offset:34816
	ds_read_b128 v[204:207], v242 offset:35840
	ds_read_b128 v[208:211], v242 offset:36864
	ds_read_b128 v[212:215], v242 offset:37888
	ds_read_b128 v[244:247], v242 offset:38912
	ds_read_b128 v[248:251], v242 offset:39936
	global_load_lds_dwordx4 v[216:217], off
	v_lshl_add_u64 v[216:217], s[34:35], 0, v[174:175]
	s_mov_b32 m0, s51
	s_nop 0
	global_load_lds_dwordx4 v[216:217], off
	s_waitcnt vmcnt(8)
	s_waitcnt lgkmcnt(0)
	s_barrier
	v_mfma_f32_16x16x32_bf16 v[8:11], v[136:139], v[168:171], v[8:11]
	v_mfma_f32_16x16x32_bf16 v[128:131], v[144:147], v[168:171], v[128:131]
	v_mfma_f32_16x16x32_bf16 v[124:127], v[136:139], v[192:195], v[124:127]
	v_mfma_f32_16x16x32_bf16 v[120:123], v[144:147], v[192:195], v[120:123]
	v_mfma_f32_16x16x32_bf16 v[116:119], v[136:139], v[208:211], v[116:119]
	v_mfma_f32_16x16x32_bf16 v[112:115], v[144:147], v[208:211], v[112:115]
	v_mfma_f32_16x16x32_bf16 v[108:111], v[136:139], v[244:247], v[108:111]
	v_mfma_f32_16x16x32_bf16 v[104:107], v[144:147], v[244:247], v[104:107]
	v_mfma_f32_16x16x32_bf16 v[8:11], v[140:143], v[188:191], v[8:11]
	v_mfma_f32_16x16x32_bf16 v[128:131], v[148:151], v[188:191], v[128:131]
	v_mfma_f32_16x16x32_bf16 v[124:127], v[140:143], v[204:207], v[124:127]
	v_mfma_f32_16x16x32_bf16 v[120:123], v[148:151], v[204:207], v[120:123]
	v_mfma_f32_16x16x32_bf16 v[116:119], v[140:143], v[212:215], v[116:119]
	v_mfma_f32_16x16x32_bf16 v[112:115], v[148:151], v[212:215], v[112:115]
	v_mfma_f32_16x16x32_bf16 v[108:111], v[140:143], v[248:251], v[108:111]
	v_mfma_f32_16x16x32_bf16 v[104:107], v[148:151], v[248:251], v[104:107]
	v_mfma_f32_16x16x32_bf16 v[100:103], v[152:155], v[168:171], v[100:103]
	v_mfma_f32_16x16x32_bf16 v[96:99], v[160:163], v[168:171], v[96:99]
	v_mfma_f32_16x16x32_bf16 v[92:95], v[152:155], v[192:195], v[92:95]
	v_mfma_f32_16x16x32_bf16 v[88:91], v[160:163], v[192:195], v[88:91]
	v_mfma_f32_16x16x32_bf16 v[84:87], v[152:155], v[208:211], v[84:87]
	v_mfma_f32_16x16x32_bf16 v[80:83], v[160:163], v[208:211], v[80:83]
	v_mfma_f32_16x16x32_bf16 v[76:79], v[152:155], v[244:247], v[76:79]
	v_mfma_f32_16x16x32_bf16 v[72:75], v[160:163], v[244:247], v[72:75]
	v_mfma_f32_16x16x32_bf16 v[100:103], v[156:159], v[188:191], v[100:103]
	v_mfma_f32_16x16x32_bf16 v[96:99], v[164:167], v[188:191], v[96:99]
	v_mfma_f32_16x16x32_bf16 v[92:95], v[156:159], v[204:207], v[92:95]
	v_mfma_f32_16x16x32_bf16 v[88:91], v[164:167], v[204:207], v[88:91]
	v_mfma_f32_16x16x32_bf16 v[84:87], v[156:159], v[212:215], v[84:87]
	v_mfma_f32_16x16x32_bf16 v[80:83], v[164:167], v[212:215], v[80:83]
	v_mfma_f32_16x16x32_bf16 v[76:79], v[156:159], v[248:251], v[76:79]
	v_mfma_f32_16x16x32_bf16 v[72:75], v[164:167], v[248:251], v[72:75]
	s_barrier
	s_add_i32 s34, s81, s38
	v_lshl_add_u64 v[196:197], v[196:197], 0, s[70:71]
	s_mov_b32 m0, s34
	ds_read_b128 v[168:171], v242 offset:49152
	ds_read_b128 v[188:191], v242 offset:50176
	ds_read_b128 v[192:195], v242 offset:51200
	ds_read_b128 v[204:207], v242 offset:52224
	ds_read_b128 v[208:211], v242 offset:53248
	ds_read_b128 v[212:215], v242 offset:54272
	ds_read_b128 v[244:247], v242 offset:55296
	ds_read_b128 v[248:251], v242 offset:56320
	global_load_lds_dwordx4 v[196:197], off
	s_add_i32 m0, s34, 0x2000
	s_add_u32 s12, s12, 0x80080
	v_lshl_add_u64 v[196:197], v[198:199], 0, s[70:71]
	s_addc_u32 s13, s13, 0
	s_add_i32 s34, s83, s38
	global_load_lds_dwordx4 v[196:197], off
	v_lshl_add_u64 v[196:197], s[12:13], 0, v[172:173]
	s_mov_b32 m0, s34
	s_nop 0
	global_load_lds_dwordx4 v[196:197], off
	v_lshl_add_u64 v[196:197], s[12:13], 0, v[176:177]
	s_add_i32 m0, s34, 0x2000
	s_nop 0
	global_load_lds_dwordx4 v[196:197], off
	v_lshl_add_u64 v[196:197], v[200:201], 0, s[70:71]
	s_mov_b32 m0, s74
	s_nop 0
	global_load_lds_dwordx4 v[196:197], off
	v_lshl_add_u64 v[196:197], v[202:203], 0, s[70:71]
	s_mov_b32 m0, s75
	s_nop 0
	global_load_lds_dwordx4 v[196:197], off
	s_waitcnt vmcnt(8)
	s_waitcnt lgkmcnt(0)
	s_barrier
	v_mfma_f32_16x16x32_bf16 v[68:71], v[136:139], v[168:171], v[68:71]
	v_mfma_f32_16x16x32_bf16 v[64:67], v[144:147], v[168:171], v[64:67]
	v_mfma_f32_16x16x32_bf16 v[60:63], v[136:139], v[192:195], v[60:63]
	v_mfma_f32_16x16x32_bf16 v[56:59], v[144:147], v[192:195], v[56:59]
	v_mfma_f32_16x16x32_bf16 v[52:55], v[136:139], v[208:211], v[52:55]
	v_mfma_f32_16x16x32_bf16 v[48:51], v[144:147], v[208:211], v[48:51]
	v_mfma_f32_16x16x32_bf16 v[44:47], v[136:139], v[244:247], v[44:47]
	v_mfma_f32_16x16x32_bf16 v[40:43], v[144:147], v[244:247], v[40:43]
	v_mfma_f32_16x16x32_bf16 v[68:71], v[140:143], v[188:191], v[68:71]
	v_mfma_f32_16x16x32_bf16 v[64:67], v[148:151], v[188:191], v[64:67]
	v_mfma_f32_16x16x32_bf16 v[60:63], v[140:143], v[204:207], v[60:63]
	v_mfma_f32_16x16x32_bf16 v[56:59], v[148:151], v[204:207], v[56:59]
	v_mfma_f32_16x16x32_bf16 v[52:55], v[140:143], v[212:215], v[52:55]
	v_mfma_f32_16x16x32_bf16 v[48:51], v[148:151], v[212:215], v[48:51]
	v_mfma_f32_16x16x32_bf16 v[44:47], v[140:143], v[248:251], v[44:47]
	v_mfma_f32_16x16x32_bf16 v[40:43], v[148:151], v[248:251], v[40:43]
	v_mfma_f32_16x16x32_bf16 v[36:39], v[152:155], v[168:171], v[36:39]
	v_mfma_f32_16x16x32_bf16 v[32:35], v[160:163], v[168:171], v[32:35]
	v_mfma_f32_16x16x32_bf16 v[28:31], v[152:155], v[192:195], v[28:31]
	v_mfma_f32_16x16x32_bf16 v[24:27], v[160:163], v[192:195], v[24:27]
	v_mfma_f32_16x16x32_bf16 v[20:23], v[152:155], v[208:211], v[20:23]
	v_mfma_f32_16x16x32_bf16 v[16:19], v[160:163], v[208:211], v[16:19]
	v_mfma_f32_16x16x32_bf16 v[12:15], v[152:155], v[244:247], v[12:15]
	v_mfma_f32_16x16x32_bf16 v[4:7], v[160:163], v[244:247], v[4:7]
	v_mfma_f32_16x16x32_bf16 v[36:39], v[156:159], v[188:191], v[36:39]
	v_mfma_f32_16x16x32_bf16 v[32:35], v[164:167], v[188:191], v[32:35]
	v_mfma_f32_16x16x32_bf16 v[28:31], v[156:159], v[204:207], v[28:31]
	v_mfma_f32_16x16x32_bf16 v[24:27], v[164:167], v[204:207], v[24:27]
	v_mfma_f32_16x16x32_bf16 v[20:23], v[156:159], v[212:215], v[20:23]
	v_mfma_f32_16x16x32_bf16 v[16:19], v[164:167], v[212:215], v[16:19]
	v_mfma_f32_16x16x32_bf16 v[12:15], v[156:159], v[248:251], v[12:15]
	v_mfma_f32_16x16x32_bf16 v[4:7], v[164:167], v[248:251], v[4:7]
	s_barrier
	s_add_i32 s42, s42, 2
	s_add_u32 s8, s8, 0x100
	s_addc_u32 s9, s9, 0
	s_cmp_gt_u32 s42, 29
	s_cbranch_scc0 .LBB0_180
	s_and_b64 vcc, exec, s[20:21]
	s_cbranch_vccz .LBB0_183
	s_barrier
.LBB0_183:
	s_setprio 0
	v_add_u32_e32 v243, s84, v229
	ds_read2_b32 v[194:195], v243 offset1:16
	ds_read2_b32 v[192:193], v243 offset0:32 offset1:48
	ds_read2_b32 v[190:191], v243 offset0:64 offset1:80
	ds_read2_b32 v[188:189], v243 offset0:96 offset1:112
	s_waitcnt lgkmcnt(0)
	v_mov_b32_e32 v143, 1.0
	s_cmp_lt_i32 s92, 8
	s_cselect_b64 s[12:13], -1, 0
	s_cmp_gt_i32 s92, 7
	v_mov_b32_e32 v142, 1.0
	v_mov_b32_e32 v141, 1.0
	v_mov_b32_e32 v140, v143
	v_mov_b32_e32 v135, 1.0
	v_mov_b32_e32 v134, 1.0
	v_mov_b32_e32 v133, 1.0
	v_mov_b32_e32 v132, v143
	s_cbranch_scc1 .LBB0_217
	s_waitcnt lgkmcnt(0)
	v_pk_mul_f32 v[132:133], v[10:11], v[194:195] op_sel_hi:[1,0]
	v_pk_mul_f32 v[134:135], v[8:9], v[194:195] op_sel_hi:[1,0]
	v_mul_f32_e32 v133, v133, v133
	v_mul_f32_e32 v135, v135, v135
	v_pk_mul_f32 v[136:137], v[130:131], v[194:195] op_sel_hi:[1,0]
	v_pk_mul_f32 v[138:139], v[128:129], v[194:195] op_sel_hi:[1,0]
	v_fmac_f32_e32 v135, v134, v134
	v_fmac_f32_e32 v133, v132, v132
	v_add_f32_e32 v132, v135, v133
	v_mul_f32_e32 v133, v139, v139
	v_mul_f32_e32 v134, v137, v137
	v_fmac_f32_e32 v133, v138, v138
	v_fmac_f32_e32 v134, v136, v136
	v_add_f32_e32 v133, v133, v134
	v_add_f32_e32 v132, v132, v133
	ds_bpermute_b32 v133, v227, v132
	s_waitcnt lgkmcnt(0)
	v_add_f32_e32 v132, v132, v133
	ds_bpermute_b32 v133, v228, v132
	s_and_saveexec_b64 s[8:9], s[4:5]
	s_cbranch_execz .LBB0_186
	s_waitcnt lgkmcnt(0)
	v_add_f32_e32 v132, v132, v133
	ds_write_b32 v234, v132

.LBB0_318:
	s_add_u32 s92, s12, 0x100
	s_addc_u32 s93, s13, 0
	s_ashr_i32 s27, s26, 31
	s_lshl_b64 s[8:9], s[26:27], 20
	s_add_u32 s30, s0, s8
	s_addc_u32 s31, s1, s9
	s_and_b64 s[8:9], s[10:11], exec
	s_cselect_b32 s27, s31, s29
	s_cselect_b32 s36, s30, s28
	s_ashr_i32 s25, s24, 31
	s_lshl_b64 s[8:9], s[24:25], 20
	s_add_u32 s34, s3, s8
	s_addc_u32 s35, s15, s9
	s_and_b64 s[8:9], s[10:11], exec
	s_cselect_b32 s25, s35, s13
	s_cselect_b32 s37, s34, s12
	s_add_u32 s8, s28, 0x80080
	s_addc_u32 s9, s29, 0
	v_lshl_add_u64 v[132:133], s[8:9], 0, v[182:183]
	v_lshl_add_u64 v[134:135], s[8:9], 0, v[184:185]
	s_mov_b32 s42, -2
	s_mov_b64 s[8:9], 0
	s_and_b64 vcc, exec, s[22:23]
	s_cbranch_vccnz .Lsp_skip_319
	s_setprio 1
.Lsp_skip_319:
.LBB0_319:
	s_add_u32 s12, s28, s8
	s_addc_u32 s13, s29, s9
	s_add_u32 s12, s12, 0x100
	s_addc_u32 s13, s13, 0
	s_add_u32 s43, s92, s8
	s_addc_u32 s66, s93, s9
	s_add_i32 s67, 0, 0x10000
	s_cmpk_eq_i32 s8, 0xf00
	s_cselect_b32 s17, s27, s13
	s_cselect_b32 s16, s36, s12
	s_cselect_b32 s13, s25, s66
	s_cselect_b32 s12, s37, s43
	s_add_i32 s43, 0, 0x14000
	v_add_u32_e32 v148, s67, v229
	v_add_u32_e32 v164, s43, v229
	ds_read_b128 v[136:139], v148
	ds_read_b128 v[140:143], v148 offset:1024
	ds_read_b128 v[144:147], v148 offset:2048
	ds_read_b128 v[148:151], v148 offset:3072
	ds_read_b128 v[152:155], v164
	ds_read_b128 v[156:159], v164 offset:1024
	ds_read_b128 v[160:163], v164 offset:2048
	ds_read_b128 v[164:167], v164 offset:3072
	v_lshl_add_u64 v[194:195], v[132:133], 0, s[8:9]
	s_add_i32 m0, s39, 0xc000
	ds_read_b128 v[168:171], v242
	ds_read_b128 v[186:189], v242 offset:1024
	ds_read_b128 v[190:193], v242 offset:2048
	ds_read_b128 v[204:207], v242 offset:3072
	ds_read_b128 v[208:211], v242 offset:4096
	ds_read_b128 v[212:215], v242 offset:5120
	ds_read_b128 v[244:247], v242 offset:6144
	ds_read_b128 v[248:251], v242 offset:7168
	global_load_lds_dwordx4 v[194:195], off
	v_lshl_add_u64 v[194:195], v[134:135], 0, s[8:9]
	s_add_i32 m0, s39, 0xe000
	s_nop 0
	global_load_lds_dwordx4 v[194:195], off
	s_waitcnt vmcnt(8)
	s_waitcnt lgkmcnt(0)
	s_barrier
	v_mfma_f32_16x16x32_bf16 v[8:11], v[136:139], v[168:171], v[8:11]
	v_mfma_f32_16x16x32_bf16 v[128:131], v[144:147], v[168:171], v[128:131]
	v_mfma_f32_16x16x32_bf16 v[124:127], v[136:139], v[190:193], v[124:127]
	v_mfma_f32_16x16x32_bf16 v[120:123], v[144:147], v[190:193], v[120:123]
	v_mfma_f32_16x16x32_bf16 v[116:119], v[136:139], v[208:211], v[116:119]
	v_mfma_f32_16x16x32_bf16 v[112:115], v[144:147], v[208:211], v[112:115]
	v_mfma_f32_16x16x32_bf16 v[108:111], v[136:139], v[244:247], v[108:111]
	v_mfma_f32_16x16x32_bf16 v[104:107], v[144:147], v[244:247], v[104:107]
	v_mfma_f32_16x16x32_bf16 v[8:11], v[140:143], v[186:189], v[8:11]
	v_mfma_f32_16x16x32_bf16 v[128:131], v[148:151], v[186:189], v[128:131]
	v_mfma_f32_16x16x32_bf16 v[124:127], v[140:143], v[204:207], v[124:127]
	v_mfma_f32_16x16x32_bf16 v[120:123], v[148:151], v[204:207], v[120:123]
	v_mfma_f32_16x16x32_bf16 v[116:119], v[140:143], v[212:215], v[116:119]
	v_mfma_f32_16x16x32_bf16 v[112:115], v[148:151], v[212:215], v[112:115]
	v_mfma_f32_16x16x32_bf16 v[108:111], v[140:143], v[248:251], v[108:111]
	v_mfma_f32_16x16x32_bf16 v[104:107], v[148:151], v[248:251], v[104:107]
	v_mfma_f32_16x16x32_bf16 v[100:103], v[152:155], v[168:171], v[100:103]
	v_mfma_f32_16x16x32_bf16 v[96:99], v[160:163], v[168:171], v[96:99]
	v_mfma_f32_16x16x32_bf16 v[92:95], v[152:155], v[190:193], v[92:95]
	v_mfma_f32_16x16x32_bf16 v[88:91], v[160:163], v[190:193], v[88:91]
	v_mfma_f32_16x16x32_bf16 v[84:87], v[152:155], v[208:211], v[84:87]
	v_mfma_f32_16x16x32_bf16 v[80:83], v[160:163], v[208:211], v[80:83]
	v_mfma_f32_16x16x32_bf16 v[76:79], v[152:155], v[244:247], v[76:79]
	v_mfma_f32_16x16x32_bf16 v[72:75], v[160:163], v[244:247], v[72:75]
	v_mfma_f32_16x16x32_bf16 v[100:103], v[156:159], v[186:189], v[100:103]
	v_mfma_f32_16x16x32_bf16 v[96:99], v[164:167], v[186:189], v[96:99]
	v_mfma_f32_16x16x32_bf16 v[92:95], v[156:159], v[204:207], v[92:95]
	v_mfma_f32_16x16x32_bf16 v[88:91], v[164:167], v[204:207], v[88:91]
	v_mfma_f32_16x16x32_bf16 v[84:87], v[156:159], v[212:215], v[84:87]
	v_mfma_f32_16x16x32_bf16 v[80:83], v[164:167], v[212:215], v[80:83]
	v_mfma_f32_16x16x32_bf16 v[76:79], v[156:159], v[248:251], v[76:79]
	v_mfma_f32_16x16x32_bf16 v[72:75], v[164:167], v[248:251], v[72:75]
	s_barrier
	s_add_i32 s66, s67, s38
	v_lshl_add_u64 v[194:195], s[12:13], 0, v[172:173]
	s_mov_b32 m0, s66
	ds_read_b128 v[168:171], v242 offset:16384
	ds_read_b128 v[186:189], v242 offset:17408
	ds_read_b128 v[190:193], v242 offset:18432
	ds_read_b128 v[204:207], v242 offset:19456
	ds_read_b128 v[208:211], v242 offset:20480
	ds_read_b128 v[212:215], v242 offset:21504
	ds_read_b128 v[244:247], v242 offset:22528
	ds_read_b128 v[248:251], v242 offset:23552
	global_load_lds_dwordx4 v[194:195], off
	s_add_i32 m0, s66, 0x2000
	s_add_u32 s66, s12, 0x80000
	v_lshl_add_u64 v[196:197], s[12:13], 0, v[176:177]
	s_addc_u32 s67, s13, 0
	s_add_i32 s43, s43, s38
	global_load_lds_dwordx4 v[196:197], off
	v_lshl_add_u64 v[198:199], s[66:67], 0, v[172:173]
	s_mov_b32 m0, s43
	v_lshl_add_u64 v[200:201], s[16:17], 0, v[174:175]
	global_load_lds_dwordx4 v[198:199], off
	v_lshl_add_u64 v[198:199], s[66:67], 0, v[176:177]
	s_add_i32 m0, s43, 0x2000
	s_nop 0
	global_load_lds_dwordx4 v[198:199], off
	v_lshl_add_u64 v[198:199], s[16:17], 0, v[0:1]
	s_mov_b32 m0, s39
	s_nop 0
	global_load_lds_dwordx4 v[198:199], off
	s_mov_b32 m0, s46
	s_nop 0
	global_load_lds_dwordx4 v[200:201], off
	s_waitcnt vmcnt(8)
	s_waitcnt lgkmcnt(0)
	s_barrier
	v_mfma_f32_16x16x32_bf16 v[68:71], v[136:139], v[168:171], v[68:71]
	v_mfma_f32_16x16x32_bf16 v[64:67], v[144:147], v[168:171], v[64:67]
	v_mfma_f32_16x16x32_bf16 v[60:63], v[136:139], v[190:193], v[60:63]
	v_mfma_f32_16x16x32_bf16 v[56:59], v[144:147], v[190:193], v[56:59]
	v_mfma_f32_16x16x32_bf16 v[52:55], v[136:139], v[208:211], v[52:55]
	v_mfma_f32_16x16x32_bf16 v[48:51], v[144:147], v[208:211], v[48:51]
	v_mfma_f32_16x16x32_bf16 v[44:47], v[136:139], v[244:247], v[44:47]
	v_mfma_f32_16x16x32_bf16 v[40:43], v[144:147], v[244:247], v[40:43]
	v_mfma_f32_16x16x32_bf16 v[68:71], v[140:143], v[186:189], v[68:71]
	v_mfma_f32_16x16x32_bf16 v[64:67], v[148:151], v[186:189], v[64:67]
	v_mfma_f32_16x16x32_bf16 v[60:63], v[140:143], v[204:207], v[60:63]
	v_mfma_f32_16x16x32_bf16 v[56:59], v[148:151], v[204:207], v[56:59]
	v_mfma_f32_16x16x32_bf16 v[52:55], v[140:143], v[212:215], v[52:55]
	v_mfma_f32_16x16x32_bf16 v[48:51], v[148:151], v[212:215], v[48:51]
	v_mfma_f32_16x16x32_bf16 v[44:47], v[140:143], v[248:251], v[44:47]
	v_mfma_f32_16x16x32_bf16 v[40:43], v[148:151], v[248:251], v[40:43]
	v_mfma_f32_16x16x32_bf16 v[36:39], v[152:155], v[168:171], v[36:39]
	v_mfma_f32_16x16x32_bf16 v[32:35], v[160:163], v[168:171], v[32:35]
	v_mfma_f32_16x16x32_bf16 v[28:31], v[152:155], v[190:193], v[28:31]
	v_mfma_f32_16x16x32_bf16 v[24:27], v[160:163], v[190:193], v[24:27]
	v_mfma_f32_16x16x32_bf16 v[20:23], v[152:155], v[208:211], v[20:23]
	v_mfma_f32_16x16x32_bf16 v[16:19], v[160:163], v[208:211], v[16:19]
	v_mfma_f32_16x16x32_bf16 v[12:15], v[152:155], v[244:247], v[12:15]
	v_mfma_f32_16x16x32_bf16 v[4:7], v[160:163], v[244:247], v[4:7]
	v_mfma_f32_16x16x32_bf16 v[36:39], v[156:159], v[186:189], v[36:39]
	v_mfma_f32_16x16x32_bf16 v[32:35], v[164:167], v[186:189], v[32:35]
	v_mfma_f32_16x16x32_bf16 v[28:31], v[156:159], v[204:207], v[28:31]
	v_mfma_f32_16x16x32_bf16 v[24:27], v[164:167], v[204:207], v[24:27]
	v_mfma_f32_16x16x32_bf16 v[20:23], v[156:159], v[212:215], v[20:23]
	v_mfma_f32_16x16x32_bf16 v[16:19], v[164:167], v[212:215], v[16:19]
	v_mfma_f32_16x16x32_bf16 v[12:15], v[156:159], v[248:251], v[12:15]
	v_mfma_f32_16x16x32_bf16 v[4:7], v[164:167], v[248:251], v[4:7]
	s_barrier
	s_add_i32 s43, 0, 0x18000
	s_add_i32 s66, 0, 0x1c000
	v_add_u32_e32 v148, s43, v229
	v_add_u32_e32 v164, s66, v229
	ds_read_b128 v[136:139], v148
	ds_read_b128 v[140:143], v148 offset:1024
	ds_read_b128 v[144:147], v148 offset:2048
	ds_read_b128 v[148:151], v148 offset:3072
	ds_read_b128 v[152:155], v164
	ds_read_b128 v[156:159], v164 offset:1024
	ds_read_b128 v[160:163], v164 offset:2048
	ds_read_b128 v[164:167], v164 offset:3072
	s_add_u32 s16, s16, 0x80000
	s_addc_u32 s17, s17, 0
	s_mov_b32 m0, s47
	v_lshl_add_u64 v[202:203], s[16:17], 0, v[0:1]
	ds_read_b128 v[168:171], v242 offset:32768
	ds_read_b128 v[186:189], v242 offset:33792
	ds_read_b128 v[190:193], v242 offset:34816
	ds_read_b128 v[204:207], v242 offset:35840
	ds_read_b128 v[208:211], v242 offset:36864
	ds_read_b128 v[212:215], v242 offset:37888
	ds_read_b128 v[244:247], v242 offset:38912
	ds_read_b128 v[248:251], v242 offset:39936
	global_load_lds_dwordx4 v[202:203], off
	v_lshl_add_u64 v[202:203], s[16:17], 0, v[174:175]
	s_mov_b32 m0, s51
	s_nop 0
	global_load_lds_dwordx4 v[202:203], off
	s_waitcnt vmcnt(8)
	s_waitcnt lgkmcnt(0)
	s_barrier
	v_mfma_f32_16x16x32_bf16 v[8:11], v[136:139], v[168:171], v[8:11]
	v_mfma_f32_16x16x32_bf16 v[128:131], v[144:147], v[168:171], v[128:131]
	v_mfma_f32_16x16x32_bf16 v[124:127], v[136:139], v[190:193], v[124:127]
	v_mfma_f32_16x16x32_bf16 v[120:123], v[144:147], v[190:193], v[120:123]
	v_mfma_f32_16x16x32_bf16 v[116:119], v[136:139], v[208:211], v[116:119]
	v_mfma_f32_16x16x32_bf16 v[112:115], v[144:147], v[208:211], v[112:115]
	v_mfma_f32_16x16x32_bf16 v[108:111], v[136:139], v[244:247], v[108:111]
	v_mfma_f32_16x16x32_bf16 v[104:107], v[144:147], v[244:247], v[104:107]
	v_mfma_f32_16x16x32_bf16 v[8:11], v[140:143], v[186:189], v[8:11]
	v_mfma_f32_16x16x32_bf16 v[128:131], v[148:151], v[186:189], v[128:131]
	v_mfma_f32_16x16x32_bf16 v[124:127], v[140:143], v[204:207], v[124:127]
	v_mfma_f32_16x16x32_bf16 v[120:123], v[148:151], v[204:207], v[120:123]
	v_mfma_f32_16x16x32_bf16 v[116:119], v[140:143], v[212:215], v[116:119]
	v_mfma_f32_16x16x32_bf16 v[112:115], v[148:151], v[212:215], v[112:115]
	v_mfma_f32_16x16x32_bf16 v[108:111], v[140:143], v[248:251], v[108:111]
	v_mfma_f32_16x16x32_bf16 v[104:107], v[148:151], v[248:251], v[104:107]
	v_mfma_f32_16x16x32_bf16 v[100:103], v[152:155], v[168:171], v[100:103]
	v_mfma_f32_16x16x32_bf16 v[96:99], v[160:163], v[168:171], v[96:99]
	v_mfma_f32_16x16x32_bf16 v[92:95], v[152:155], v[190:193], v[92:95]
	v_mfma_f32_16x16x32_bf16 v[88:91], v[160:163], v[190:193], v[88:91]
	v_mfma_f32_16x16x32_bf16 v[84:87], v[152:155], v[208:211], v[84:87]
	v_mfma_f32_16x16x32_bf16 v[80:83], v[160:163], v[208:211], v[80:83]
	v_mfma_f32_16x16x32_bf16 v[76:79], v[152:155], v[244:247], v[76:79]
	v_mfma_f32_16x16x32_bf16 v[72:75], v[160:163], v[244:247], v[72:75]
	v_mfma_f32_16x16x32_bf16 v[100:103], v[156:159], v[186:189], v[100:103]
	v_mfma_f32_16x16x32_bf16 v[96:99], v[164:167], v[186:189], v[96:99]
	v_mfma_f32_16x16x32_bf16 v[92:95], v[156:159], v[204:207], v[92:95]
	v_mfma_f32_16x16x32_bf16 v[88:91], v[164:167], v[204:207], v[88:91]
	v_mfma_f32_16x16x32_bf16 v[84:87], v[156:159], v[212:215], v[84:87]
	v_mfma_f32_16x16x32_bf16 v[80:83], v[164:167], v[212:215], v[80:83]
	v_mfma_f32_16x16x32_bf16 v[76:79], v[156:159], v[248:251], v[76:79]
	v_mfma_f32_16x16x32_bf16 v[72:75], v[164:167], v[248:251], v[72:75]
	s_barrier
	s_add_i32 s16, s43, s38
	v_lshl_add_u64 v[194:195], v[194:195], 0, s[70:71]
	s_mov_b32 m0, s16
	ds_read_b128 v[168:171], v242 offset:49152
	ds_read_b128 v[186:189], v242 offset:50176
	ds_read_b128 v[190:193], v242 offset:51200
	ds_read_b128 v[204:207], v242 offset:52224
	ds_read_b128 v[208:211], v242 offset:53248
	ds_read_b128 v[212:215], v242 offset:54272
	ds_read_b128 v[244:247], v242 offset:55296
	ds_read_b128 v[248:251], v242 offset:56320
	global_load_lds_dwordx4 v[194:195], off
	s_add_i32 m0, s16, 0x2000
	s_add_u32 s12, s12, 0x80080
	v_lshl_add_u64 v[194:195], v[196:197], 0, s[70:71]
	s_addc_u32 s13, s13, 0
	s_add_i32 s16, s66, s38
	global_load_lds_dwordx4 v[194:195], off
	v_lshl_add_u64 v[194:195], s[12:13], 0, v[172:173]
	s_mov_b32 m0, s16
	s_nop 0
	global_load_lds_dwordx4 v[194:195], off
	v_lshl_add_u64 v[194:195], s[12:13], 0, v[176:177]
	s_add_i32 m0, s16, 0x2000
	s_nop 0
	global_load_lds_dwordx4 v[194:195], off
	v_lshl_add_u64 v[194:195], v[198:199], 0, s[70:71]
	s_mov_b32 m0, s52
	s_nop 0
	global_load_lds_dwordx4 v[194:195], off
	v_lshl_add_u64 v[194:195], v[200:201], 0, s[70:71]
	s_mov_b32 m0, s54
	s_nop 0
	global_load_lds_dwordx4 v[194:195], off
	s_waitcnt vmcnt(8)
	s_waitcnt lgkmcnt(0)
	s_barrier
	v_mfma_f32_16x16x32_bf16 v[68:71], v[136:139], v[168:171], v[68:71]
	v_mfma_f32_16x16x32_bf16 v[64:67], v[144:147], v[168:171], v[64:67]
	v_mfma_f32_16x16x32_bf16 v[60:63], v[136:139], v[190:193], v[60:63]
	v_mfma_f32_16x16x32_bf16 v[56:59], v[144:147], v[190:193], v[56:59]
	v_mfma_f32_16x16x32_bf16 v[52:55], v[136:139], v[208:211], v[52:55]
	v_mfma_f32_16x16x32_bf16 v[48:51], v[144:147], v[208:211], v[48:51]
	v_mfma_f32_16x16x32_bf16 v[44:47], v[136:139], v[244:247], v[44:47]
	v_mfma_f32_16x16x32_bf16 v[40:43], v[144:147], v[244:247], v[40:43]
	v_mfma_f32_16x16x32_bf16 v[68:71], v[140:143], v[186:189], v[68:71]
	v_mfma_f32_16x16x32_bf16 v[64:67], v[148:151], v[186:189], v[64:67]
	v_mfma_f32_16x16x32_bf16 v[60:63], v[140:143], v[204:207], v[60:63]
	v_mfma_f32_16x16x32_bf16 v[56:59], v[148:151], v[204:207], v[56:59]
	v_mfma_f32_16x16x32_bf16 v[52:55], v[140:143], v[212:215], v[52:55]
	v_mfma_f32_16x16x32_bf16 v[48:51], v[148:151], v[212:215], v[48:51]
	v_mfma_f32_16x16x32_bf16 v[44:47], v[140:143], v[248:251], v[44:47]
	v_mfma_f32_16x16x32_bf16 v[40:43], v[148:151], v[248:251], v[40:43]
	v_mfma_f32_16x16x32_bf16 v[36:39], v[152:155], v[168:171], v[36:39]
	v_mfma_f32_16x16x32_bf16 v[32:35], v[160:163], v[168:171], v[32:35]
	v_mfma_f32_16x16x32_bf16 v[28:31], v[152:155], v[190:193], v[28:31]
	v_mfma_f32_16x16x32_bf16 v[24:27], v[160:163], v[190:193], v[24:27]
	v_mfma_f32_16x16x32_bf16 v[20:23], v[152:155], v[208:211], v[20:23]
	v_mfma_f32_16x16x32_bf16 v[16:19], v[160:163], v[208:211], v[16:19]
	v_mfma_f32_16x16x32_bf16 v[12:15], v[152:155], v[244:247], v[12:15]
	v_mfma_f32_16x16x32_bf16 v[4:7], v[160:163], v[244:247], v[4:7]
	v_mfma_f32_16x16x32_bf16 v[36:39], v[156:159], v[186:189], v[36:39]
	v_mfma_f32_16x16x32_bf16 v[32:35], v[164:167], v[186:189], v[32:35]
	v_mfma_f32_16x16x32_bf16 v[28:31], v[156:159], v[204:207], v[28:31]
	v_mfma_f32_16x16x32_bf16 v[24:27], v[164:167], v[204:207], v[24:27]
	v_mfma_f32_16x16x32_bf16 v[20:23], v[156:159], v[212:215], v[20:23]
	v_mfma_f32_16x16x32_bf16 v[16:19], v[164:167], v[212:215], v[16:19]
	v_mfma_f32_16x16x32_bf16 v[12:15], v[156:159], v[248:251], v[12:15]
	v_mfma_f32_16x16x32_bf16 v[4:7], v[164:167], v[248:251], v[4:7]
	s_barrier
	s_add_i32 s42, s42, 2
	s_add_u32 s8, s8, 0x100
	s_addc_u32 s9, s9, 0
	s_cmp_gt_u32 s42, 29
	s_cbranch_scc0 .LBB0_319
	s_and_b64 vcc, exec, s[22:23]
	s_cbranch_vccz .LBB0_322
	s_barrier
.LBB0_322:
	s_setprio 0
	v_add_u32_e32 v243, s69, v228
	ds_read2_b32 v[204:205], v243 offset1:16
	ds_read2_b32 v[194:195], v243 offset0:32 offset1:48
	ds_read2_b32 v[188:189], v243 offset0:64 offset1:80
	ds_read2_b32 v[186:187], v243 offset0:96 offset1:112
	s_cmp_lt_i32 s75, 8
	s_cselect_b64 s[12:13], -1, 0
	s_cmp_gt_i32 s75, 7
	s_waitcnt lgkmcnt(0)
	s_cselect_b64 s[16:17], -1, 0
	v_mov_b32_e32 v147, 1.0
	s_and_b64 vcc, exec, s[16:17]
	v_mov_b32_e32 v146, 1.0
	v_mov_b32_e32 v145, 1.0
	v_mov_b32_e32 v144, v147
	v_mov_b32_e32 v143, 1.0
	v_mov_b32_e32 v142, 1.0
	v_mov_b32_e32 v141, 1.0
	v_mov_b32_e32 v140, v147
	s_cbranch_vccnz .LBB0_356
	s_waitcnt lgkmcnt(0)
	v_pk_mul_f32 v[132:133], v[10:11], v[204:205] op_sel_hi:[1,0]
	v_pk_mul_f32 v[134:135], v[8:9], v[204:205] op_sel_hi:[1,0]
	v_mul_f32_e32 v133, v133, v133
	v_mul_f32_e32 v135, v135, v135
	v_pk_mul_f32 v[136:137], v[130:131], v[204:205] op_sel_hi:[1,0]
	v_pk_mul_f32 v[138:139], v[128:129], v[204:205] op_sel_hi:[1,0]
	v_fmac_f32_e32 v135, v134, v134
	v_fmac_f32_e32 v133, v132, v132
	v_add_f32_e32 v132, v135, v133
	v_mul_f32_e32 v133, v139, v139
	v_mul_f32_e32 v134, v137, v137
	v_fmac_f32_e32 v133, v138, v138
	v_fmac_f32_e32 v134, v136, v136
	v_add_f32_e32 v133, v133, v134
	v_add_f32_e32 v132, v132, v133
	ds_bpermute_b32 v133, v226, v132
	s_waitcnt lgkmcnt(0)
	v_add_f32_e32 v132, v132, v133
	ds_bpermute_b32 v133, v227, v132
	s_and_saveexec_b64 s[8:9], s[4:5]
	s_cbranch_execz .LBB0_325
	s_waitcnt lgkmcnt(0)
	v_add_f32_e32 v132, v132, v133
	ds_write_b32 v233, v132

.LBB0_802:
	s_add_u32 s84, s12, 0x100
	s_addc_u32 s85, s13, 0
	s_ashr_i32 s27, s26, 31
	s_lshl_b64 s[8:9], s[26:27], 20
	s_add_u32 s30, s47, s8
	s_addc_u32 s31, s66, s9
	s_and_b64 s[8:9], s[10:11], exec
	s_cselect_b32 s27, s31, s29
	s_cselect_b32 s42, s30, s28
	s_ashr_i32 s25, s24, 31
	s_lshl_b64 s[8:9], s[24:25], 20
	s_add_u32 s34, s67, s8
	s_addc_u32 s35, s69, s9
	s_and_b64 s[8:9], s[10:11], exec
	s_cselect_b32 s25, s35, s13
	s_cselect_b32 s43, s34, s12
	s_add_u32 s8, s28, 0x80080
	s_addc_u32 s9, s29, 0
	v_lshl_add_u64 v[132:133], s[8:9], 0, v[172:173]
	v_lshl_add_u64 v[134:135], s[8:9], 0, v[174:175]
	s_mov_b32 s52, -2
	s_mov_b64 s[8:9], 0
	s_and_b64 vcc, exec, s[22:23]
	s_cbranch_vccnz .Lsp_skip_803
	s_setprio 1
.Lsp_skip_803:
.LBB0_803:
	s_add_u32 s12, s28, s8
	s_addc_u32 s13, s29, s9
	s_add_u32 s12, s12, 0x100
	s_addc_u32 s13, s13, 0
	s_add_u32 s81, s84, s8
	s_addc_u32 s83, s85, s9
	s_add_i32 s95, 0, 0x10000
	s_cmpk_eq_i32 s8, 0xf00
	s_cselect_b32 s37, s27, s13
	s_cselect_b32 s36, s42, s12
	s_cselect_b32 s13, s25, s83
	s_cselect_b32 s12, s43, s81
	s_add_i32 s81, 0, 0x14000
	v_add_u32_e32 v148, s95, v207
	v_add_u32_e32 v176, s81, v207
	ds_read_b128 v[136:139], v148
	ds_read_b128 v[140:143], v148 offset:1024
	ds_read_b128 v[144:147], v148 offset:2048
	ds_read_b128 v[148:151], v148 offset:3072
	ds_read_b128 v[152:155], v176
	ds_read_b128 v[156:159], v176 offset:1024
	ds_read_b128 v[160:163], v176 offset:2048
	s_waitcnt lgkmcnt(0)
	ds_read_b128 v[176:179], v176 offset:3072
	v_lshl_add_u64 v[196:197], v[132:133], 0, s[8:9]
	s_add_i32 m0, s75, 0xc000
	ds_read_b128 v[180:183], v209
	ds_read_b128 v[184:187], v209 offset:1024
	ds_read_b128 v[188:191], v209 offset:2048
	ds_read_b128 v[192:195], v209 offset:3072
	ds_read_b128 v[212:215], v209 offset:4096
	ds_read_b128 v[226:229], v209 offset:5120
	ds_read_b128 v[230:233], v209 offset:6144
	ds_read_b128 v[234:237], v209 offset:7168
	global_load_lds_dwordx4 v[196:197], off
	v_lshl_add_u64 v[196:197], v[134:135], 0, s[8:9]
	s_add_i32 m0, s75, 0xe000
	s_nop 0
	global_load_lds_dwordx4 v[196:197], off
	s_waitcnt vmcnt(8)
	s_waitcnt lgkmcnt(0)
	s_barrier
	v_mfma_f32_16x16x32_bf16 v[8:11], v[136:139], v[180:183], v[8:11]
	v_mfma_f32_16x16x32_bf16 v[128:131], v[144:147], v[180:183], v[128:131]
	v_mfma_f32_16x16x32_bf16 v[124:127], v[136:139], v[188:191], v[124:127]
	v_mfma_f32_16x16x32_bf16 v[120:123], v[144:147], v[188:191], v[120:123]
	v_mfma_f32_16x16x32_bf16 v[116:119], v[136:139], v[212:215], v[116:119]
	v_mfma_f32_16x16x32_bf16 v[112:115], v[144:147], v[212:215], v[112:115]
	v_mfma_f32_16x16x32_bf16 v[108:111], v[136:139], v[230:233], v[108:111]
	v_mfma_f32_16x16x32_bf16 v[104:107], v[144:147], v[230:233], v[104:107]
	v_mfma_f32_16x16x32_bf16 v[8:11], v[140:143], v[184:187], v[8:11]
	v_mfma_f32_16x16x32_bf16 v[128:131], v[148:151], v[184:187], v[128:131]
	v_mfma_f32_16x16x32_bf16 v[124:127], v[140:143], v[192:195], v[124:127]
	v_mfma_f32_16x16x32_bf16 v[120:123], v[148:151], v[192:195], v[120:123]
	v_mfma_f32_16x16x32_bf16 v[116:119], v[140:143], v[226:229], v[116:119]
	v_mfma_f32_16x16x32_bf16 v[112:115], v[148:151], v[226:229], v[112:115]
	v_mfma_f32_16x16x32_bf16 v[108:111], v[140:143], v[234:237], v[108:111]
	v_mfma_f32_16x16x32_bf16 v[104:107], v[148:151], v[234:237], v[104:107]
	v_mfma_f32_16x16x32_bf16 v[100:103], v[152:155], v[180:183], v[100:103]
	v_mfma_f32_16x16x32_bf16 v[96:99], v[160:163], v[180:183], v[96:99]
	v_mfma_f32_16x16x32_bf16 v[92:95], v[152:155], v[188:191], v[92:95]
	v_mfma_f32_16x16x32_bf16 v[88:91], v[160:163], v[188:191], v[88:91]
	v_mfma_f32_16x16x32_bf16 v[84:87], v[152:155], v[212:215], v[84:87]
	v_mfma_f32_16x16x32_bf16 v[80:83], v[160:163], v[212:215], v[80:83]
	v_mfma_f32_16x16x32_bf16 v[76:79], v[152:155], v[230:233], v[76:79]
	v_mfma_f32_16x16x32_bf16 v[72:75], v[160:163], v[230:233], v[72:75]
	v_mfma_f32_16x16x32_bf16 v[100:103], v[156:159], v[184:187], v[100:103]
	v_mfma_f32_16x16x32_bf16 v[96:99], v[176:179], v[184:187], v[96:99]
	v_mfma_f32_16x16x32_bf16 v[92:95], v[156:159], v[192:195], v[92:95]
	v_mfma_f32_16x16x32_bf16 v[88:91], v[176:179], v[192:195], v[88:91]
	v_mfma_f32_16x16x32_bf16 v[84:87], v[156:159], v[226:229], v[84:87]
	v_mfma_f32_16x16x32_bf16 v[80:83], v[176:179], v[226:229], v[80:83]
	v_mfma_f32_16x16x32_bf16 v[76:79], v[156:159], v[234:237], v[76:79]
	v_mfma_f32_16x16x32_bf16 v[72:75], v[176:179], v[234:237], v[72:75]
	s_barrier
	s_add_i32 s83, s95, s74
	v_lshl_add_u64 v[196:197], s[12:13], 0, v[164:165]
	s_mov_b32 m0, s83
	ds_read_b128 v[180:183], v209 offset:16384
	ds_read_b128 v[184:187], v209 offset:17408
	ds_read_b128 v[188:191], v209 offset:18432
	ds_read_b128 v[192:195], v209 offset:19456
	ds_read_b128 v[212:215], v209 offset:20480
	ds_read_b128 v[226:229], v209 offset:21504
	ds_read_b128 v[230:233], v209 offset:22528
	ds_read_b128 v[234:237], v209 offset:23552
	global_load_lds_dwordx4 v[196:197], off
	s_add_i32 m0, s83, 0x2000
	s_add_u32 vcc_lo, s12, 0x80000
	v_lshl_add_u64 v[198:199], s[12:13], 0, v[168:169]
	s_addc_u32 vcc_hi, s13, 0
	s_add_i32 s81, s81, s74
	global_load_lds_dwordx4 v[198:199], off
	v_lshl_add_u64 v[200:201], vcc, 0, v[164:165]
	s_mov_b32 m0, s81
	v_lshl_add_u64 v[202:203], s[36:37], 0, v[166:167]
	global_load_lds_dwordx4 v[200:201], off
	v_lshl_add_u64 v[200:201], vcc, 0, v[168:169]
	s_add_i32 m0, s81, 0x2000
	s_nop 0
	global_load_lds_dwordx4 v[200:201], off
	v_lshl_add_u64 v[200:201], s[36:37], 0, v[0:1]
	s_mov_b32 m0, s75
	s_nop 0
	global_load_lds_dwordx4 v[200:201], off
	s_mov_b32 m0, s15
	s_nop 0
	global_load_lds_dwordx4 v[202:203], off
	s_waitcnt vmcnt(8)
	s_waitcnt lgkmcnt(0)
	s_barrier
	v_mfma_f32_16x16x32_bf16 v[68:71], v[136:139], v[180:183], v[68:71]
	v_mfma_f32_16x16x32_bf16 v[64:67], v[144:147], v[180:183], v[64:67]
	v_mfma_f32_16x16x32_bf16 v[60:63], v[136:139], v[188:191], v[60:63]
	v_mfma_f32_16x16x32_bf16 v[56:59], v[144:147], v[188:191], v[56:59]
	v_mfma_f32_16x16x32_bf16 v[52:55], v[136:139], v[212:215], v[52:55]
	v_mfma_f32_16x16x32_bf16 v[48:51], v[144:147], v[212:215], v[48:51]
	v_mfma_f32_16x16x32_bf16 v[44:47], v[136:139], v[230:233], v[44:47]
	v_mfma_f32_16x16x32_bf16 v[40:43], v[144:147], v[230:233], v[40:43]
	v_mfma_f32_16x16x32_bf16 v[68:71], v[140:143], v[184:187], v[68:71]
	v_mfma_f32_16x16x32_bf16 v[64:67], v[148:151], v[184:187], v[64:67]
	v_mfma_f32_16x16x32_bf16 v[60:63], v[140:143], v[192:195], v[60:63]
	v_mfma_f32_16x16x32_bf16 v[56:59], v[148:151], v[192:195], v[56:59]
	v_mfma_f32_16x16x32_bf16 v[52:55], v[140:143], v[226:229], v[52:55]
	v_mfma_f32_16x16x32_bf16 v[48:51], v[148:151], v[226:229], v[48:51]
	v_mfma_f32_16x16x32_bf16 v[44:47], v[140:143], v[234:237], v[44:47]
	v_mfma_f32_16x16x32_bf16 v[40:43], v[148:151], v[234:237], v[40:43]
	v_mfma_f32_16x16x32_bf16 v[36:39], v[152:155], v[180:183], v[36:39]
	v_mfma_f32_16x16x32_bf16 v[32:35], v[160:163], v[180:183], v[32:35]
	v_mfma_f32_16x16x32_bf16 v[28:31], v[152:155], v[188:191], v[28:31]
	v_mfma_f32_16x16x32_bf16 v[24:27], v[160:163], v[188:191], v[24:27]
	v_mfma_f32_16x16x32_bf16 v[20:23], v[152:155], v[212:215], v[20:23]
	v_mfma_f32_16x16x32_bf16 v[16:19], v[160:163], v[212:215], v[16:19]
	v_mfma_f32_16x16x32_bf16 v[12:15], v[152:155], v[230:233], v[12:15]
	v_mfma_f32_16x16x32_bf16 v[4:7], v[160:163], v[230:233], v[4:7]
	v_mfma_f32_16x16x32_bf16 v[36:39], v[156:159], v[184:187], v[36:39]
	v_mfma_f32_16x16x32_bf16 v[32:35], v[176:179], v[184:187], v[32:35]
	v_mfma_f32_16x16x32_bf16 v[28:31], v[156:159], v[192:195], v[28:31]
	v_mfma_f32_16x16x32_bf16 v[24:27], v[176:179], v[192:195], v[24:27]
	v_mfma_f32_16x16x32_bf16 v[20:23], v[156:159], v[226:229], v[20:23]
	v_mfma_f32_16x16x32_bf16 v[16:19], v[176:179], v[226:229], v[16:19]
	v_mfma_f32_16x16x32_bf16 v[12:15], v[156:159], v[234:237], v[12:15]
	v_mfma_f32_16x16x32_bf16 v[4:7], v[176:179], v[234:237], v[4:7]
	s_barrier
	s_add_i32 s81, 0, 0x18000
	s_add_i32 s83, 0, 0x1c000
	v_add_u32_e32 v148, s81, v207
	v_add_u32_e32 v176, s83, v207
	ds_read_b128 v[136:139], v148
	ds_read_b128 v[140:143], v148 offset:1024
	ds_read_b128 v[144:147], v148 offset:2048
	ds_read_b128 v[148:151], v148 offset:3072
	ds_read_b128 v[152:155], v176
	ds_read_b128 v[156:159], v176 offset:1024
	ds_read_b128 v[160:163], v176 offset:2048
	ds_read_b128 v[176:179], v176 offset:3072
	s_add_u32 s36, s36, 0x80000
	s_addc_u32 s37, s37, 0
	s_mov_b32 m0, s38
	v_lshl_add_u64 v[216:217], s[36:37], 0, v[0:1]
	ds_read_b128 v[180:183], v209 offset:32768
	ds_read_b128 v[184:187], v209 offset:33792
	ds_read_b128 v[188:191], v209 offset:34816
	ds_read_b128 v[192:195], v209 offset:35840
	ds_read_b128 v[212:215], v209 offset:36864
	ds_read_b128 v[226:229], v209 offset:37888
	ds_read_b128 v[230:233], v209 offset:38912
	ds_read_b128 v[234:237], v209 offset:39936
	global_load_lds_dwordx4 v[216:217], off
	v_lshl_add_u64 v[216:217], s[36:37], 0, v[166:167]
	s_mov_b32 m0, s39
	s_nop 0
	global_load_lds_dwordx4 v[216:217], off
	s_waitcnt vmcnt(8)
	s_waitcnt lgkmcnt(0)
	s_barrier
	v_mfma_f32_16x16x32_bf16 v[8:11], v[136:139], v[180:183], v[8:11]
	v_mfma_f32_16x16x32_bf16 v[128:131], v[144:147], v[180:183], v[128:131]
	v_mfma_f32_16x16x32_bf16 v[124:127], v[136:139], v[188:191], v[124:127]
	v_mfma_f32_16x16x32_bf16 v[120:123], v[144:147], v[188:191], v[120:123]
	v_mfma_f32_16x16x32_bf16 v[116:119], v[136:139], v[212:215], v[116:119]
	v_mfma_f32_16x16x32_bf16 v[112:115], v[144:147], v[212:215], v[112:115]
	v_mfma_f32_16x16x32_bf16 v[108:111], v[136:139], v[230:233], v[108:111]
	v_mfma_f32_16x16x32_bf16 v[104:107], v[144:147], v[230:233], v[104:107]
	v_mfma_f32_16x16x32_bf16 v[8:11], v[140:143], v[184:187], v[8:11]
	v_mfma_f32_16x16x32_bf16 v[128:131], v[148:151], v[184:187], v[128:131]
	v_mfma_f32_16x16x32_bf16 v[124:127], v[140:143], v[192:195], v[124:127]
	v_mfma_f32_16x16x32_bf16 v[120:123], v[148:151], v[192:195], v[120:123]
	v_mfma_f32_16x16x32_bf16 v[116:119], v[140:143], v[226:229], v[116:119]
	v_mfma_f32_16x16x32_bf16 v[112:115], v[148:151], v[226:229], v[112:115]
	v_mfma_f32_16x16x32_bf16 v[108:111], v[140:143], v[234:237], v[108:111]
	v_mfma_f32_16x16x32_bf16 v[104:107], v[148:151], v[234:237], v[104:107]
	v_mfma_f32_16x16x32_bf16 v[100:103], v[152:155], v[180:183], v[100:103]
	v_mfma_f32_16x16x32_bf16 v[96:99], v[160:163], v[180:183], v[96:99]
	v_mfma_f32_16x16x32_bf16 v[92:95], v[152:155], v[188:191], v[92:95]
	v_mfma_f32_16x16x32_bf16 v[88:91], v[160:163], v[188:191], v[88:91]
	v_mfma_f32_16x16x32_bf16 v[84:87], v[152:155], v[212:215], v[84:87]
	v_mfma_f32_16x16x32_bf16 v[80:83], v[160:163], v[212:215], v[80:83]
	v_mfma_f32_16x16x32_bf16 v[76:79], v[152:155], v[230:233], v[76:79]
	v_mfma_f32_16x16x32_bf16 v[72:75], v[160:163], v[230:233], v[72:75]
	v_mfma_f32_16x16x32_bf16 v[100:103], v[156:159], v[184:187], v[100:103]
	v_mfma_f32_16x16x32_bf16 v[96:99], v[176:179], v[184:187], v[96:99]
	v_mfma_f32_16x16x32_bf16 v[92:95], v[156:159], v[192:195], v[92:95]
	v_mfma_f32_16x16x32_bf16 v[88:91], v[176:179], v[192:195], v[88:91]
	v_mfma_f32_16x16x32_bf16 v[84:87], v[156:159], v[226:229], v[84:87]
	v_mfma_f32_16x16x32_bf16 v[80:83], v[176:179], v[226:229], v[80:83]
	v_mfma_f32_16x16x32_bf16 v[76:79], v[156:159], v[234:237], v[76:79]
	v_mfma_f32_16x16x32_bf16 v[72:75], v[176:179], v[234:237], v[72:75]
	s_barrier
	s_add_i32 s36, s81, s74
	v_lshl_add_u64 v[196:197], v[196:197], 0, s[70:71]
	s_mov_b32 m0, s36
	ds_read_b128 v[180:183], v209 offset:49152
	ds_read_b128 v[184:187], v209 offset:50176
	ds_read_b128 v[188:191], v209 offset:51200
	ds_read_b128 v[192:195], v209 offset:52224
	ds_read_b128 v[212:215], v209 offset:53248
	ds_read_b128 v[226:229], v209 offset:54272
	ds_read_b128 v[230:233], v209 offset:55296
	ds_read_b128 v[234:237], v209 offset:56320
	global_load_lds_dwordx4 v[196:197], off
	s_add_i32 m0, s36, 0x2000
	s_add_u32 s12, s12, 0x80080
	v_lshl_add_u64 v[196:197], v[198:199], 0, s[70:71]
	s_addc_u32 s13, s13, 0
	s_add_i32 s36, s83, s74
	global_load_lds_dwordx4 v[196:197], off
	v_lshl_add_u64 v[196:197], s[12:13], 0, v[164:165]
	s_mov_b32 m0, s36
	s_nop 0
	global_load_lds_dwordx4 v[196:197], off
	v_lshl_add_u64 v[196:197], s[12:13], 0, v[168:169]
	s_add_i32 m0, s36, 0x2000
	s_nop 0
	global_load_lds_dwordx4 v[196:197], off
	v_lshl_add_u64 v[196:197], v[200:201], 0, s[70:71]
	s_mov_b32 m0, s51
	s_nop 0
	global_load_lds_dwordx4 v[196:197], off
	v_lshl_add_u64 v[196:197], v[202:203], 0, s[70:71]
	s_mov_b32 m0, s92
	s_nop 0
	global_load_lds_dwordx4 v[196:197], off
	s_waitcnt vmcnt(8)
	s_waitcnt lgkmcnt(0)
	s_barrier
	v_mfma_f32_16x16x32_bf16 v[68:71], v[136:139], v[180:183], v[68:71]
	v_mfma_f32_16x16x32_bf16 v[64:67], v[144:147], v[180:183], v[64:67]
	v_mfma_f32_16x16x32_bf16 v[60:63], v[136:139], v[188:191], v[60:63]
	v_mfma_f32_16x16x32_bf16 v[56:59], v[144:147], v[188:191], v[56:59]
	v_mfma_f32_16x16x32_bf16 v[52:55], v[136:139], v[212:215], v[52:55]
	v_mfma_f32_16x16x32_bf16 v[48:51], v[144:147], v[212:215], v[48:51]
	v_mfma_f32_16x16x32_bf16 v[44:47], v[136:139], v[230:233], v[44:47]
	v_mfma_f32_16x16x32_bf16 v[40:43], v[144:147], v[230:233], v[40:43]
	v_mfma_f32_16x16x32_bf16 v[68:71], v[140:143], v[184:187], v[68:71]
	v_mfma_f32_16x16x32_bf16 v[64:67], v[148:151], v[184:187], v[64:67]
	v_mfma_f32_16x16x32_bf16 v[60:63], v[140:143], v[192:195], v[60:63]
	v_mfma_f32_16x16x32_bf16 v[56:59], v[148:151], v[192:195], v[56:59]
	v_mfma_f32_16x16x32_bf16 v[52:55], v[140:143], v[226:229], v[52:55]
	v_mfma_f32_16x16x32_bf16 v[48:51], v[148:151], v[226:229], v[48:51]
	v_mfma_f32_16x16x32_bf16 v[44:47], v[140:143], v[234:237], v[44:47]
	v_mfma_f32_16x16x32_bf16 v[40:43], v[148:151], v[234:237], v[40:43]
	v_mfma_f32_16x16x32_bf16 v[36:39], v[152:155], v[180:183], v[36:39]
	v_mfma_f32_16x16x32_bf16 v[32:35], v[160:163], v[180:183], v[32:35]
	v_mfma_f32_16x16x32_bf16 v[28:31], v[152:155], v[188:191], v[28:31]
	v_mfma_f32_16x16x32_bf16 v[24:27], v[160:163], v[188:191], v[24:27]
	v_mfma_f32_16x16x32_bf16 v[20:23], v[152:155], v[212:215], v[20:23]
	v_mfma_f32_16x16x32_bf16 v[16:19], v[160:163], v[212:215], v[16:19]
	v_mfma_f32_16x16x32_bf16 v[12:15], v[152:155], v[230:233], v[12:15]
	v_mfma_f32_16x16x32_bf16 v[4:7], v[160:163], v[230:233], v[4:7]
	v_mfma_f32_16x16x32_bf16 v[36:39], v[156:159], v[184:187], v[36:39]
	v_mfma_f32_16x16x32_bf16 v[32:35], v[176:179], v[184:187], v[32:35]
	v_mfma_f32_16x16x32_bf16 v[28:31], v[156:159], v[192:195], v[28:31]
	v_mfma_f32_16x16x32_bf16 v[24:27], v[176:179], v[192:195], v[24:27]
	v_mfma_f32_16x16x32_bf16 v[20:23], v[156:159], v[226:229], v[20:23]
	v_mfma_f32_16x16x32_bf16 v[16:19], v[176:179], v[226:229], v[16:19]
	v_mfma_f32_16x16x32_bf16 v[12:15], v[156:159], v[234:237], v[12:15]
	v_mfma_f32_16x16x32_bf16 v[4:7], v[176:179], v[234:237], v[4:7]
	s_barrier
	s_add_i32 s52, s52, 2
	s_add_u32 s8, s8, 0x100
	s_addc_u32 s9, s9, 0
	s_cmp_gt_u32 s52, 29
	s_cbranch_scc0 .LBB0_803
	s_and_b64 vcc, exec, s[22:23]
	s_cbranch_vccz .LBB0_806
	s_barrier
.LBB0_806:
	s_setprio 0
	v_add_u32_e32 v211, s93, v206
	ds_read2_b32 v[186:187], v211 offset1:16
	ds_read2_b32 v[184:185], v211 offset0:32 offset1:48
	ds_read2_b32 v[182:183], v211 offset0:64 offset1:80
	ds_read2_b32 v[176:177], v211 offset0:96 offset1:112
	s_waitcnt lgkmcnt(0)
	s_lshl_b32 s81, s26, 8
	v_cndmask_b32_e64 v132, 0, 1, s[10:11]
	s_or_b32 s43, s81, 16
	s_or_b32 s27, s81, 32
	s_or_b32 s25, s81, 48
	v_mov_b32_e32 v156, 0
	v_cmp_ne_u32_e64 s[8:9], 1, v132
	s_andn2_b64 vcc, exec, s[10:11]
	v_mov_b32_e32 v157, 0
	v_mov_b32_e32 v158, 0
	v_mov_b32_e32 v159, 0
	v_mov_b32_e32 v160, 0
	v_mov_b32_e32 v161, 0
	v_mov_b32_e32 v162, 0
	v_mov_b32_e32 v163, 0
	v_mov_b32_e32 v148, 0
	v_mov_b32_e32 v149, 0
	v_mov_b32_e32 v150, 0
	v_mov_b32_e32 v151, 0
	v_mov_b32_e32 v152, 0
	v_mov_b32_e32 v153, 0
	v_mov_b32_e32 v154, 0
	v_mov_b32_e32 v155, 0
	v_mov_b32_e32 v140, 0
	v_mov_b32_e32 v141, 0
	v_mov_b32_e32 v142, 0
	v_mov_b32_e32 v143, 0
	v_mov_b32_e32 v144, 0
	v_mov_b32_e32 v145, 0
	v_mov_b32_e32 v146, 0
	v_mov_b32_e32 v147, 0
	v_mov_b32_e32 v132, 0
	v_mov_b32_e32 v133, 0
	v_mov_b32_e32 v134, 0
	v_mov_b32_e32 v135, 0
	v_mov_b32_e32 v136, 0
	v_mov_b32_e32 v137, 0
	v_mov_b32_e32 v138, 0
	v_mov_b32_e32 v139, 0
	s_cbranch_vccnz .LBB0_808
	s_cmp_eq_u32 s26, s3
	s_cbranch_scc1 .LBB0_808
	v_add_u32_e32 v132, s81, v3
	v_ashrrev_i32_e32 v133, 31, v132
	v_lshlrev_b64 v[132:133], 7, v[132:133]
	v_lshl_add_u64 v[132:133], v[170:171], 0, v[132:133]
	global_load_dwordx4 v[156:159], v[132:133], off
	global_load_dwordx4 v[160:163], v[132:133], off offset:16
	v_add_u32_e32 v132, s43, v3
	v_ashrrev_i32_e32 v133, 31, v132
	v_lshlrev_b64 v[132:133], 7, v[132:133]
	v_lshl_add_u64 v[132:133], v[170:171], 0, v[132:133]
	global_load_dwordx4 v[148:151], v[132:133], off
	global_load_dwordx4 v[152:155], v[132:133], off offset:16
	v_add_u32_e32 v132, s27, v3
	v_ashrrev_i32_e32 v133, 31, v132
	v_lshlrev_b64 v[132:133], 7, v[132:133]
	v_lshl_add_u64 v[132:133], v[170:171], 0, v[132:133]
	global_load_dwordx4 v[140:143], v[132:133], off
	global_load_dwordx4 v[144:147], v[132:133], off offset:16
	v_add_u32_e32 v132, s25, v3
	v_ashrrev_i32_e32 v133, 31, v132
	v_lshlrev_b64 v[132:133], 7, v[132:133]
	v_lshl_add_u64 v[136:137], v[170:171], 0, v[132:133]
	global_load_dwordx4 v[132:135], v[136:137], off
	s_nop 0
	global_load_dwordx4 v[136:139], v[136:137], off offset:16

.LBB0_974:
	s_ashr_i32 s25, s24, 31
	s_lshl_b64 s[26:27], s[24:25], 20
	s_add_u32 s26, s1, s26
	s_addc_u32 s27, s3, s27
	s_and_b64 s[28:29], s[8:9], exec
	s_cselect_b32 s25, s27, s31
	s_cselect_b32 s66, s26, s30
	s_ashr_i32 s23, s22, 31
	s_lshl_b64 s[28:29], s[22:23], 20
	s_add_u32 s28, s10, s28
	s_addc_u32 s29, s11, s29
	s_and_b64 s[36:37], s[8:9], exec
	s_cselect_b32 s23, s29, s35
	s_cselect_b32 s67, s28, s34
	s_add_u32 s30, s30, 0x80080
	s_addc_u32 s31, s31, 0
	s_add_u32 s69, s34, 0x100
	v_mov_b32_e32 v4, 0
	s_addc_u32 s74, s35, 0
	s_mov_b32 s75, -2
	s_waitcnt lgkmcnt(0)
	v_mov_b32_e32 v5, v4
	v_mov_b32_e32 v6, v4
	v_mov_b32_e32 v7, v4
	v_mov_b32_e32 v8, v4
	v_mov_b32_e32 v9, v4
	v_mov_b32_e32 v10, v4
	v_mov_b32_e32 v11, v4
	v_mov_b32_e32 v20, v4
	v_mov_b32_e32 v21, v4
	v_mov_b32_e32 v22, v4
	v_mov_b32_e32 v23, v4
	v_mov_b32_e32 v24, v4
	v_mov_b32_e32 v25, v4
	v_mov_b32_e32 v26, v4
	v_mov_b32_e32 v27, v4
	v_mov_b32_e32 v36, v4
	v_mov_b32_e32 v37, v4
	v_mov_b32_e32 v38, v4
	v_mov_b32_e32 v39, v4
	v_mov_b32_e32 v40, v4
	v_mov_b32_e32 v41, v4
	v_mov_b32_e32 v42, v4
	v_mov_b32_e32 v43, v4
	v_mov_b32_e32 v52, v4
	v_mov_b32_e32 v53, v4
	v_mov_b32_e32 v54, v4
	v_mov_b32_e32 v55, v4
	v_mov_b32_e32 v56, v4
	v_mov_b32_e32 v57, v4
	v_mov_b32_e32 v58, v4
	v_mov_b32_e32 v59, v4
	v_mov_b32_e32 v12, v4
	v_mov_b32_e32 v13, v4
	v_mov_b32_e32 v14, v4
	v_mov_b32_e32 v15, v4
	v_mov_b32_e32 v16, v4
	v_mov_b32_e32 v17, v4
	v_mov_b32_e32 v18, v4
	v_mov_b32_e32 v19, v4
	v_mov_b32_e32 v28, v4
	v_mov_b32_e32 v29, v4
	v_mov_b32_e32 v30, v4
	v_mov_b32_e32 v31, v4
	v_mov_b32_e32 v32, v4
	v_mov_b32_e32 v33, v4
	v_mov_b32_e32 v34, v4
	v_mov_b32_e32 v35, v4
	v_mov_b32_e32 v44, v4
	v_mov_b32_e32 v45, v4
	v_mov_b32_e32 v46, v4
	v_mov_b32_e32 v47, v4
	v_mov_b32_e32 v48, v4
	v_mov_b32_e32 v49, v4
	v_mov_b32_e32 v50, v4
	v_mov_b32_e32 v51, v4
	v_mov_b32_e32 v60, v4
	v_mov_b32_e32 v61, v4
	v_mov_b32_e32 v62, v4
	v_mov_b32_e32 v63, v4
	v_mov_b32_e32 v64, v4
	v_mov_b32_e32 v65, v4
	v_mov_b32_e32 v66, v4
	v_mov_b32_e32 v67, v4
	v_mov_b32_e32 v68, v4
	v_mov_b32_e32 v69, v4
	v_mov_b32_e32 v70, v4
	v_mov_b32_e32 v71, v4
	v_mov_b32_e32 v72, v4
	v_mov_b32_e32 v73, v4
	v_mov_b32_e32 v74, v4
	v_mov_b32_e32 v75, v4
	v_mov_b32_e32 v84, v4
	v_mov_b32_e32 v85, v4
	v_mov_b32_e32 v86, v4
	v_mov_b32_e32 v87, v4
	v_mov_b32_e32 v88, v4
	v_mov_b32_e32 v89, v4
	v_mov_b32_e32 v90, v4
	v_mov_b32_e32 v91, v4
	v_mov_b32_e32 v100, v4
	v_mov_b32_e32 v101, v4
	v_mov_b32_e32 v102, v4
	v_mov_b32_e32 v103, v4
	v_mov_b32_e32 v104, v4
	v_mov_b32_e32 v105, v4
	v_mov_b32_e32 v106, v4
	v_mov_b32_e32 v107, v4
	v_mov_b32_e32 v116, v4
	v_mov_b32_e32 v117, v4
	v_mov_b32_e32 v118, v4
	v_mov_b32_e32 v119, v4
	v_mov_b32_e32 v120, v4
	v_mov_b32_e32 v121, v4
	v_mov_b32_e32 v122, v4
	v_mov_b32_e32 v123, v4
	v_mov_b32_e32 v76, v4
	v_mov_b32_e32 v77, v4
	v_mov_b32_e32 v78, v4
	v_mov_b32_e32 v79, v4
	v_mov_b32_e32 v80, v4
	v_mov_b32_e32 v81, v4
	v_mov_b32_e32 v82, v4
	v_mov_b32_e32 v83, v4
	v_mov_b32_e32 v92, v4
	v_mov_b32_e32 v93, v4
	v_mov_b32_e32 v94, v4
	v_mov_b32_e32 v95, v4
	v_mov_b32_e32 v96, v4
	v_mov_b32_e32 v97, v4
	v_mov_b32_e32 v98, v4
	v_mov_b32_e32 v99, v4
	v_mov_b32_e32 v108, v4
	v_mov_b32_e32 v109, v4
	v_mov_b32_e32 v110, v4
	v_mov_b32_e32 v111, v4
	v_mov_b32_e32 v112, v4
	v_mov_b32_e32 v113, v4
	v_mov_b32_e32 v114, v4
	v_mov_b32_e32 v115, v4
	v_mov_b32_e32 v124, v4
	v_mov_b32_e32 v125, v4
	v_mov_b32_e32 v126, v4
	v_mov_b32_e32 v127, v4
	v_mov_b32_e32 v128, v4
	v_mov_b32_e32 v129, v4
	v_mov_b32_e32 v130, v4
	v_mov_b32_e32 v131, v4
	s_and_b64 vcc, exec, s[20:21]
	s_cbranch_vccnz .Lsp_skip_975
	s_setprio 1
.Lsp_skip_975:
.LBB0_975:
	s_add_u32 s34, s30, 0xfff80080
	s_addc_u32 s35, s31, -1
	s_add_i32 s81, 0, 0x10000
	s_cmp_eq_u32 s75, 28
	s_cselect_b32 s37, s25, s35
	s_cselect_b32 s36, s66, s34
	s_cselect_b32 s35, s23, s74
	s_cselect_b32 s34, s67, s69
	s_add_i32 s83, 0, 0x14000
	v_add_u32_e32 v144, s81, v182
	v_add_u32_e32 v170, s83, v182
	ds_read_b128 v[132:135], v144
	ds_read_b128 v[136:139], v144 offset:1024
	ds_read_b128 v[140:143], v144 offset:2048
	ds_read_b128 v[144:147], v144 offset:3072
	ds_read_b128 v[148:151], v170
	ds_read_b128 v[152:155], v170 offset:1024
	ds_read_b128 v[156:159], v170 offset:2048
	ds_read_b128 v[170:173], v170 offset:3072
	v_lshl_add_u64 v[212:213], s[30:31], 0, v[166:167]
	s_add_i32 m0, s15, 0xc000
	ds_read_b128 v[174:177], v186
	ds_read_b128 v[178:181], v186 offset:1024
	ds_read_b128 v[188:191], v186 offset:2048
	ds_read_b128 v[192:195], v186 offset:3072
	ds_read_b128 v[196:199], v186 offset:4096
	ds_read_b128 v[200:203], v186 offset:5120
	ds_read_b128 v[204:207], v186 offset:6144
	ds_read_b128 v[208:211], v186 offset:7168
	global_load_lds_dwordx4 v[212:213], off
	v_lshl_add_u64 v[212:213], s[30:31], 0, v[168:169]
	s_add_i32 m0, s15, 0xe000
	s_nop 0
	global_load_lds_dwordx4 v[212:213], off
	s_waitcnt vmcnt(8)
	s_waitcnt lgkmcnt(0)
	s_barrier
	v_mfma_f32_16x16x32_bf16 v[128:131], v[132:135], v[174:177], v[128:131]
	v_mfma_f32_16x16x32_bf16 v[124:127], v[140:143], v[174:177], v[124:127]
	v_mfma_f32_16x16x32_bf16 v[112:115], v[132:135], v[188:191], v[112:115]
	v_mfma_f32_16x16x32_bf16 v[108:111], v[140:143], v[188:191], v[108:111]
	v_mfma_f32_16x16x32_bf16 v[96:99], v[132:135], v[196:199], v[96:99]
	v_mfma_f32_16x16x32_bf16 v[92:95], v[140:143], v[196:199], v[92:95]
	v_mfma_f32_16x16x32_bf16 v[80:83], v[132:135], v[204:207], v[80:83]
	v_mfma_f32_16x16x32_bf16 v[76:79], v[140:143], v[204:207], v[76:79]
	v_mfma_f32_16x16x32_bf16 v[128:131], v[136:139], v[178:181], v[128:131]
	v_mfma_f32_16x16x32_bf16 v[124:127], v[144:147], v[178:181], v[124:127]
	v_mfma_f32_16x16x32_bf16 v[112:115], v[136:139], v[192:195], v[112:115]
	v_mfma_f32_16x16x32_bf16 v[108:111], v[144:147], v[192:195], v[108:111]
	v_mfma_f32_16x16x32_bf16 v[96:99], v[136:139], v[200:203], v[96:99]
	v_mfma_f32_16x16x32_bf16 v[92:95], v[144:147], v[200:203], v[92:95]
	v_mfma_f32_16x16x32_bf16 v[80:83], v[136:139], v[208:211], v[80:83]
	v_mfma_f32_16x16x32_bf16 v[76:79], v[144:147], v[208:211], v[76:79]
	v_mfma_f32_16x16x32_bf16 v[120:123], v[148:151], v[174:177], v[120:123]
	v_mfma_f32_16x16x32_bf16 v[116:119], v[156:159], v[174:177], v[116:119]
	v_mfma_f32_16x16x32_bf16 v[104:107], v[148:151], v[188:191], v[104:107]
	v_mfma_f32_16x16x32_bf16 v[100:103], v[156:159], v[188:191], v[100:103]
	v_mfma_f32_16x16x32_bf16 v[88:91], v[148:151], v[196:199], v[88:91]
	v_mfma_f32_16x16x32_bf16 v[84:87], v[156:159], v[196:199], v[84:87]
	v_mfma_f32_16x16x32_bf16 v[72:75], v[148:151], v[204:207], v[72:75]
	v_mfma_f32_16x16x32_bf16 v[68:71], v[156:159], v[204:207], v[68:71]
	v_mfma_f32_16x16x32_bf16 v[120:123], v[152:155], v[178:181], v[120:123]
	v_mfma_f32_16x16x32_bf16 v[116:119], v[170:173], v[178:181], v[116:119]
	v_mfma_f32_16x16x32_bf16 v[104:107], v[152:155], v[192:195], v[104:107]
	v_mfma_f32_16x16x32_bf16 v[100:103], v[170:173], v[192:195], v[100:103]
	v_mfma_f32_16x16x32_bf16 v[88:91], v[152:155], v[200:203], v[88:91]
	v_mfma_f32_16x16x32_bf16 v[84:87], v[170:173], v[200:203], v[84:87]
	v_mfma_f32_16x16x32_bf16 v[72:75], v[152:155], v[208:211], v[72:75]
	v_mfma_f32_16x16x32_bf16 v[68:71], v[170:173], v[208:211], v[68:71]
	s_barrier
	s_add_i32 s81, s81, s0
	v_lshl_add_u64 v[212:213], s[34:35], 0, v[162:163]
	s_mov_b32 m0, s81
	ds_read_b128 v[174:177], v186 offset:16384
	ds_read_b128 v[178:181], v186 offset:17408
	ds_read_b128 v[188:191], v186 offset:18432
	ds_read_b128 v[192:195], v186 offset:19456
	ds_read_b128 v[196:199], v186 offset:20480
	ds_read_b128 v[200:203], v186 offset:21504
	ds_read_b128 v[204:207], v186 offset:22528
	ds_read_b128 v[208:211], v186 offset:23552
	global_load_lds_dwordx4 v[212:213], off
	s_add_i32 m0, s81, 0x2000
	s_add_u32 s84, s34, 0x80000
	v_lshl_add_u64 v[214:215], s[34:35], 0, v[0:1]
	s_addc_u32 s85, s35, 0
	s_add_i32 s81, s83, s0
	global_load_lds_dwordx4 v[214:215], off
	v_lshl_add_u64 v[216:217], s[84:85], 0, v[162:163]
	s_mov_b32 m0, s81
	v_lshl_add_u64 v[226:227], s[36:37], 0, v[160:161]
	global_load_lds_dwordx4 v[216:217], off
	v_lshl_add_u64 v[216:217], s[84:85], 0, v[0:1]
	s_add_i32 m0, s81, 0x2000
	s_nop 0
	global_load_lds_dwordx4 v[216:217], off
	v_lshl_add_u64 v[216:217], s[36:37], 0, v[164:165]
	s_mov_b32 m0, s15
	s_nop 0
	global_load_lds_dwordx4 v[216:217], off
	s_mov_b32 m0, s38
	s_nop 0
	global_load_lds_dwordx4 v[226:227], off
	s_waitcnt vmcnt(8)
	s_waitcnt lgkmcnt(0)
	s_barrier
	v_mfma_f32_16x16x32_bf16 v[64:67], v[132:135], v[174:177], v[64:67]
	v_mfma_f32_16x16x32_bf16 v[60:63], v[140:143], v[174:177], v[60:63]
	v_mfma_f32_16x16x32_bf16 v[48:51], v[132:135], v[188:191], v[48:51]
	v_mfma_f32_16x16x32_bf16 v[44:47], v[140:143], v[188:191], v[44:47]
	v_mfma_f32_16x16x32_bf16 v[32:35], v[132:135], v[196:199], v[32:35]
	v_mfma_f32_16x16x32_bf16 v[28:31], v[140:143], v[196:199], v[28:31]
	v_mfma_f32_16x16x32_bf16 v[16:19], v[132:135], v[204:207], v[16:19]
	v_mfma_f32_16x16x32_bf16 v[12:15], v[140:143], v[204:207], v[12:15]
	v_mfma_f32_16x16x32_bf16 v[64:67], v[136:139], v[178:181], v[64:67]
	v_mfma_f32_16x16x32_bf16 v[60:63], v[144:147], v[178:181], v[60:63]
	v_mfma_f32_16x16x32_bf16 v[48:51], v[136:139], v[192:195], v[48:51]
	v_mfma_f32_16x16x32_bf16 v[44:47], v[144:147], v[192:195], v[44:47]
	v_mfma_f32_16x16x32_bf16 v[32:35], v[136:139], v[200:203], v[32:35]
	v_mfma_f32_16x16x32_bf16 v[28:31], v[144:147], v[200:203], v[28:31]
	v_mfma_f32_16x16x32_bf16 v[16:19], v[136:139], v[208:211], v[16:19]
	v_mfma_f32_16x16x32_bf16 v[12:15], v[144:147], v[208:211], v[12:15]
	v_mfma_f32_16x16x32_bf16 v[56:59], v[148:151], v[174:177], v[56:59]
	v_mfma_f32_16x16x32_bf16 v[52:55], v[156:159], v[174:177], v[52:55]
	v_mfma_f32_16x16x32_bf16 v[40:43], v[148:151], v[188:191], v[40:43]
	v_mfma_f32_16x16x32_bf16 v[36:39], v[156:159], v[188:191], v[36:39]
	v_mfma_f32_16x16x32_bf16 v[24:27], v[148:151], v[196:199], v[24:27]
	v_mfma_f32_16x16x32_bf16 v[20:23], v[156:159], v[196:199], v[20:23]
	v_mfma_f32_16x16x32_bf16 v[8:11], v[148:151], v[204:207], v[8:11]
	v_mfma_f32_16x16x32_bf16 v[4:7], v[156:159], v[204:207], v[4:7]
	v_mfma_f32_16x16x32_bf16 v[56:59], v[152:155], v[178:181], v[56:59]
	v_mfma_f32_16x16x32_bf16 v[52:55], v[170:173], v[178:181], v[52:55]
	v_mfma_f32_16x16x32_bf16 v[40:43], v[152:155], v[192:195], v[40:43]
	v_mfma_f32_16x16x32_bf16 v[36:39], v[170:173], v[192:195], v[36:39]
	v_mfma_f32_16x16x32_bf16 v[24:27], v[152:155], v[200:203], v[24:27]
	v_mfma_f32_16x16x32_bf16 v[20:23], v[170:173], v[200:203], v[20:23]
	v_mfma_f32_16x16x32_bf16 v[8:11], v[152:155], v[208:211], v[8:11]
	v_mfma_f32_16x16x32_bf16 v[4:7], v[170:173], v[208:211], v[4:7]
	s_barrier
	s_add_i32 s81, 0, 0x18000
	s_add_i32 s83, 0, 0x1c000
	v_add_u32_e32 v144, s81, v182
	v_add_u32_e32 v170, s83, v182
	ds_read_b128 v[132:135], v144
	ds_read_b128 v[136:139], v144 offset:1024
	ds_read_b128 v[140:143], v144 offset:2048
	ds_read_b128 v[144:147], v144 offset:3072
	ds_read_b128 v[148:151], v170
	ds_read_b128 v[152:155], v170 offset:1024
	ds_read_b128 v[156:159], v170 offset:2048
	ds_read_b128 v[170:173], v170 offset:3072
	s_add_u32 s36, s36, 0x80000
	s_addc_u32 s37, s37, 0
	s_mov_b32 m0, s39
	v_lshl_add_u64 v[228:229], s[36:37], 0, v[164:165]
	ds_read_b128 v[174:177], v186 offset:32768
	ds_read_b128 v[178:181], v186 offset:33792
	ds_read_b128 v[188:191], v186 offset:34816
	ds_read_b128 v[192:195], v186 offset:35840
	ds_read_b128 v[196:199], v186 offset:36864
	ds_read_b128 v[200:203], v186 offset:37888
	ds_read_b128 v[204:207], v186 offset:38912
	ds_read_b128 v[208:211], v186 offset:39936
	global_load_lds_dwordx4 v[228:229], off
	v_lshl_add_u64 v[228:229], s[36:37], 0, v[160:161]
	s_mov_b32 m0, s43
	s_nop 0
	global_load_lds_dwordx4 v[228:229], off
	s_waitcnt vmcnt(8)
	s_waitcnt lgkmcnt(0)
	s_barrier
	v_mfma_f32_16x16x32_bf16 v[128:131], v[132:135], v[174:177], v[128:131]
	v_mfma_f32_16x16x32_bf16 v[124:127], v[140:143], v[174:177], v[124:127]
	v_mfma_f32_16x16x32_bf16 v[112:115], v[132:135], v[188:191], v[112:115]
	v_mfma_f32_16x16x32_bf16 v[108:111], v[140:143], v[188:191], v[108:111]
	v_mfma_f32_16x16x32_bf16 v[96:99], v[132:135], v[196:199], v[96:99]
	v_mfma_f32_16x16x32_bf16 v[92:95], v[140:143], v[196:199], v[92:95]
	v_mfma_f32_16x16x32_bf16 v[80:83], v[132:135], v[204:207], v[80:83]
	v_mfma_f32_16x16x32_bf16 v[76:79], v[140:143], v[204:207], v[76:79]
	v_mfma_f32_16x16x32_bf16 v[128:131], v[136:139], v[178:181], v[128:131]
	v_mfma_f32_16x16x32_bf16 v[124:127], v[144:147], v[178:181], v[124:127]
	v_mfma_f32_16x16x32_bf16 v[112:115], v[136:139], v[192:195], v[112:115]
	v_mfma_f32_16x16x32_bf16 v[108:111], v[144:147], v[192:195], v[108:111]
	v_mfma_f32_16x16x32_bf16 v[96:99], v[136:139], v[200:203], v[96:99]
	v_mfma_f32_16x16x32_bf16 v[92:95], v[144:147], v[200:203], v[92:95]
	v_mfma_f32_16x16x32_bf16 v[80:83], v[136:139], v[208:211], v[80:83]
	v_mfma_f32_16x16x32_bf16 v[76:79], v[144:147], v[208:211], v[76:79]
	v_mfma_f32_16x16x32_bf16 v[120:123], v[148:151], v[174:177], v[120:123]
	v_mfma_f32_16x16x32_bf16 v[116:119], v[156:159], v[174:177], v[116:119]
	v_mfma_f32_16x16x32_bf16 v[104:107], v[148:151], v[188:191], v[104:107]
	v_mfma_f32_16x16x32_bf16 v[100:103], v[156:159], v[188:191], v[100:103]
	v_mfma_f32_16x16x32_bf16 v[88:91], v[148:151], v[196:199], v[88:91]
	v_mfma_f32_16x16x32_bf16 v[84:87], v[156:159], v[196:199], v[84:87]
	v_mfma_f32_16x16x32_bf16 v[72:75], v[148:151], v[204:207], v[72:75]
	v_mfma_f32_16x16x32_bf16 v[68:71], v[156:159], v[204:207], v[68:71]
	v_mfma_f32_16x16x32_bf16 v[120:123], v[152:155], v[178:181], v[120:123]
	v_mfma_f32_16x16x32_bf16 v[116:119], v[170:173], v[178:181], v[116:119]
	v_mfma_f32_16x16x32_bf16 v[104:107], v[152:155], v[192:195], v[104:107]
	v_mfma_f32_16x16x32_bf16 v[100:103], v[170:173], v[192:195], v[100:103]
	v_mfma_f32_16x16x32_bf16 v[88:91], v[152:155], v[200:203], v[88:91]
	v_mfma_f32_16x16x32_bf16 v[84:87], v[170:173], v[200:203], v[84:87]
	v_mfma_f32_16x16x32_bf16 v[72:75], v[152:155], v[208:211], v[72:75]
	v_mfma_f32_16x16x32_bf16 v[68:71], v[170:173], v[208:211], v[68:71]
	s_barrier
	s_add_i32 s36, s81, s0
	v_lshl_add_u64 v[212:213], v[212:213], 0, s[70:71]
	s_mov_b32 m0, s36
	ds_read_b128 v[174:177], v186 offset:49152
	ds_read_b128 v[178:181], v186 offset:50176
	ds_read_b128 v[188:191], v186 offset:51200
	ds_read_b128 v[192:195], v186 offset:52224
	ds_read_b128 v[196:199], v186 offset:53248
	ds_read_b128 v[200:203], v186 offset:54272
	ds_read_b128 v[204:207], v186 offset:55296
	ds_read_b128 v[208:211], v186 offset:56320
	global_load_lds_dwordx4 v[212:213], off
	s_add_i32 m0, s36, 0x2000
	s_add_u32 s34, s34, 0x80080
	v_lshl_add_u64 v[212:213], v[214:215], 0, s[70:71]
	s_addc_u32 s35, s35, 0
	s_add_i32 s36, s83, s0
	global_load_lds_dwordx4 v[212:213], off
	v_lshl_add_u64 v[212:213], s[34:35], 0, v[162:163]
	s_mov_b32 m0, s36
	s_nop 0
	global_load_lds_dwordx4 v[212:213], off
	v_lshl_add_u64 v[212:213], s[34:35], 0, v[0:1]
	s_add_i32 m0, s36, 0x2000
	s_nop 0
	global_load_lds_dwordx4 v[212:213], off
	v_lshl_add_u64 v[212:213], v[216:217], 0, s[70:71]
	s_mov_b32 m0, s47
	s_nop 0
	global_load_lds_dwordx4 v[212:213], off
	v_lshl_add_u64 v[212:213], v[226:227], 0, s[70:71]
	s_mov_b32 m0, s51
	s_nop 0
	global_load_lds_dwordx4 v[212:213], off
	s_waitcnt vmcnt(8)
	s_waitcnt lgkmcnt(0)
	s_barrier
	v_mfma_f32_16x16x32_bf16 v[64:67], v[132:135], v[174:177], v[64:67]
	v_mfma_f32_16x16x32_bf16 v[60:63], v[140:143], v[174:177], v[60:63]
	v_mfma_f32_16x16x32_bf16 v[48:51], v[132:135], v[188:191], v[48:51]
	v_mfma_f32_16x16x32_bf16 v[44:47], v[140:143], v[188:191], v[44:47]
	v_mfma_f32_16x16x32_bf16 v[32:35], v[132:135], v[196:199], v[32:35]
	v_mfma_f32_16x16x32_bf16 v[28:31], v[140:143], v[196:199], v[28:31]
	v_mfma_f32_16x16x32_bf16 v[16:19], v[132:135], v[204:207], v[16:19]
	v_mfma_f32_16x16x32_bf16 v[12:15], v[140:143], v[204:207], v[12:15]
	v_mfma_f32_16x16x32_bf16 v[64:67], v[136:139], v[178:181], v[64:67]
	v_mfma_f32_16x16x32_bf16 v[60:63], v[144:147], v[178:181], v[60:63]
	v_mfma_f32_16x16x32_bf16 v[48:51], v[136:139], v[192:195], v[48:51]
	v_mfma_f32_16x16x32_bf16 v[44:47], v[144:147], v[192:195], v[44:47]
	v_mfma_f32_16x16x32_bf16 v[32:35], v[136:139], v[200:203], v[32:35]
	v_mfma_f32_16x16x32_bf16 v[28:31], v[144:147], v[200:203], v[28:31]
	v_mfma_f32_16x16x32_bf16 v[16:19], v[136:139], v[208:211], v[16:19]
	v_mfma_f32_16x16x32_bf16 v[12:15], v[144:147], v[208:211], v[12:15]
	v_mfma_f32_16x16x32_bf16 v[56:59], v[148:151], v[174:177], v[56:59]
	v_mfma_f32_16x16x32_bf16 v[52:55], v[156:159], v[174:177], v[52:55]
	v_mfma_f32_16x16x32_bf16 v[40:43], v[148:151], v[188:191], v[40:43]
	v_mfma_f32_16x16x32_bf16 v[36:39], v[156:159], v[188:191], v[36:39]
	v_mfma_f32_16x16x32_bf16 v[24:27], v[148:151], v[196:199], v[24:27]
	v_mfma_f32_16x16x32_bf16 v[20:23], v[156:159], v[196:199], v[20:23]
	v_mfma_f32_16x16x32_bf16 v[8:11], v[148:151], v[204:207], v[8:11]
	v_mfma_f32_16x16x32_bf16 v[4:7], v[156:159], v[204:207], v[4:7]
	v_mfma_f32_16x16x32_bf16 v[56:59], v[152:155], v[178:181], v[56:59]
	v_mfma_f32_16x16x32_bf16 v[52:55], v[170:173], v[178:181], v[52:55]
	v_mfma_f32_16x16x32_bf16 v[40:43], v[152:155], v[192:195], v[40:43]
	v_mfma_f32_16x16x32_bf16 v[36:39], v[170:173], v[192:195], v[36:39]
	v_mfma_f32_16x16x32_bf16 v[24:27], v[152:155], v[200:203], v[24:27]
	v_mfma_f32_16x16x32_bf16 v[20:23], v[170:173], v[200:203], v[20:23]
	v_mfma_f32_16x16x32_bf16 v[8:11], v[152:155], v[208:211], v[8:11]
	v_mfma_f32_16x16x32_bf16 v[4:7], v[170:173], v[208:211], v[4:7]
	s_barrier
	s_add_i32 s75, s75, 2
	s_add_u32 s30, s30, 0x100
	s_addc_u32 s31, s31, 0
	s_add_u32 s69, s69, 0x100
	s_addc_u32 s74, s74, 0
	s_cmp_gt_u32 s75, 29
	s_cbranch_scc0 .LBB0_975
	s_and_b64 vcc, exec, s[20:21]
	s_cbranch_vccz .LBB0_978
	s_barrier
.LBB0_978:
	s_setprio 0
	v_lshl_or_b32 v170, s42, 8, v183
	v_lshl_add_u32 v172, s52, 8, v3
	v_ashrrev_i32_e32 v171, 31, v170
	v_lshlrev_b64 v[192:193], 1, v[170:171]
	v_ashrrev_i32_e32 v173, 31, v172
	v_lshl_add_u64 v[174:175], s[16:17], 0, v[192:193]
	v_lshlrev_b64 v[194:195], 12, v[172:173]
	v_lshl_add_u64 v[132:133], v[174:175], 0, v[194:195]
	global_load_dwordx4 v[188:191], v[132:133], off
	global_load_dwordx4 v[156:159], v[132:133], off offset:256
	v_or_b32_e32 v180, 16, v172
	v_ashrrev_i32_e32 v181, 31, v180
	v_lshlrev_b64 v[132:133], 12, v[180:181]
	v_or_b32_e32 v178, 32, v172
	v_lshl_add_u64 v[132:133], v[174:175], 0, v[132:133]
	v_ashrrev_i32_e32 v179, 31, v178
	global_load_dwordx4 v[152:155], v[132:133], off
	global_load_dwordx4 v[148:151], v[132:133], off offset:256
	v_lshlrev_b64 v[132:133], 12, v[178:179]
	v_or_b32_e32 v176, 48, v172
	v_lshl_add_u64 v[132:133], v[174:175], 0, v[132:133]
	v_ashrrev_i32_e32 v177, 31, v176
	global_load_dwordx4 v[144:147], v[132:133], off
	global_load_dwordx4 v[140:143], v[132:133], off offset:256
	v_lshlrev_b64 v[132:133], 12, v[176:177]
	v_lshl_add_u64 v[132:133], v[174:175], 0, v[132:133]
	global_load_dwordx4 v[136:139], v[132:133], off
	s_nop 0
	global_load_dwordx4 v[132:135], v[132:133], off offset:256
	v_lshl_add_u64 v[194:195], s[16:17], 0, v[194:195]
	v_lshl_add_u64 v[192:193], v[194:195], 0, v[192:193]
	s_lshl_b32 s30, s42, 2
	s_ashr_i32 s31, s30, 31
	s_waitcnt vmcnt(0)
	v_lshlrev_b32_e32 v196, 16, v188
	v_and_b32_e32 v197, 0xffff0000, v188
	v_lshlrev_b32_e32 v188, 16, v189
	v_and_b32_e32 v189, 0xffff0000, v189
	v_pk_add_f32 v[130:131], v[130:131], v[188:189]
	v_lshlrev_b32_e32 v188, 16, v190
	v_and_b32_e32 v189, 0xffff0000, v190
	v_pk_add_f32 v[128:129], v[128:129], v[196:197]
	v_lshlrev_b32_e32 v190, 16, v191
	v_and_b32_e32 v191, 0xffff0000, v191
	v_pk_add_f32 v[188:189], v[124:125], v[188:189]
	v_cvt_pk_bf16_f32 v124, v128, v129
	v_cvt_pk_bf16_f32 v125, v130, v131
	v_pk_add_f32 v[190:191], v[126:127], v[190:191]
	v_cvt_pk_bf16_f32 v126, v188, v189
	s_nop 0
	v_cvt_pk_bf16_f32 v127, v190, v191
	global_store_dwordx4 v[192:193], v[124:127], off
	s_nop 1
	v_mul_f32_e32 v124, v129, v129
	v_mul_f32_e32 v125, v131, v131
	v_fmac_f32_e32 v124, v128, v128
	v_fmac_f32_e32 v125, v130, v130
	v_add_f32_e32 v124, v124, v125
	v_mul_f32_e32 v125, v189, v189
	v_mul_f32_e32 v126, v191, v191
	v_fmac_f32_e32 v125, v188, v188
	v_fmac_f32_e32 v126, v190, v190
	v_add_f32_e32 v125, v125, v126
	v_add_f32_e32 v128, v124, v125
	v_lshlrev_b32_e32 v124, 16, v156
	v_and_b32_e32 v125, 0xffff0000, v156
	v_lshlrev_b32_e32 v126, 16, v157
	v_and_b32_e32 v127, 0xffff0000, v157
	v_pk_add_f32 v[120:121], v[120:121], v[124:125]
	v_lshlrev_b32_e32 v124, 16, v158
	v_and_b32_e32 v125, 0xffff0000, v158
	v_pk_add_f32 v[122:123], v[122:123], v[126:127]
	v_lshlrev_b32_e32 v126, 16, v159
	v_and_b32_e32 v127, 0xffff0000, v159
	v_pk_add_f32 v[124:125], v[116:117], v[124:125]
	v_cvt_pk_bf16_f32 v116, v120, v121
	v_cvt_pk_bf16_f32 v117, v122, v123
	v_pk_add_f32 v[126:127], v[118:119], v[126:127]
	v_cvt_pk_bf16_f32 v118, v124, v125
	s_nop 0
	v_cvt_pk_bf16_f32 v119, v126, v127
	global_store_dwordx4 v[192:193], v[116:119], off offset:256
	s_nop 1
	v_mul_f32_e32 v116, v121, v121
	v_mul_f32_e32 v117, v123, v123
	v_fmac_f32_e32 v116, v120, v120
	v_fmac_f32_e32 v117, v122, v122
	v_add_f32_e32 v116, v116, v117
	v_mul_f32_e32 v117, v125, v125
	v_mul_f32_e32 v118, v127, v127
	v_fmac_f32_e32 v117, v124, v124
	v_fmac_f32_e32 v118, v126, v126
	v_add_f32_e32 v117, v117, v118
	v_add_f32_e32 v116, v116, v117
	v_add_f32_e32 v116, v128, v116
	ds_bpermute_b32 v117, v184, v116
	s_waitcnt lgkmcnt(0)
	v_add_f32_e32 v116, v116, v117
	ds_bpermute_b32 v117, v185, v116
	s_and_saveexec_b64 s[34:35], s[6:7]
	s_cbranch_execz .LBB0_980
	v_lshlrev_b64 v[118:119], 7, v[172:173]
	v_lshl_add_u64 v[118:119], s[18:19], 0, v[118:119]
	v_lshl_add_u64 v[118:119], s[30:31], 2, v[118:119]
	s_lshl_b32 s52, s46, 2
	v_lshl_add_u64 v[118:119], v[118:119], 0, s[52:53]
	s_waitcnt lgkmcnt(0)
	v_add_f32_e32 v116, v116, v117
	global_store_dword v[118:119], v116, off

.LBB0_1066:
	s_add_u32 s42, s34, 0x100
	s_addc_u32 s75, s35, 0
	s_ashr_i32 s25, s24, 31
	s_lshl_b64 s[12:13], s[24:25], 20
	s_add_u32 s28, s0, s12
	s_addc_u32 s29, s1, s13
	s_and_b64 s[12:13], s[10:11], exec
	s_cselect_b32 s25, s29, s27
	s_cselect_b32 s81, s28, s26
	s_ashr_i32 s23, s22, 31
	s_lshl_b64 s[12:13], s[22:23], 20
	s_add_u32 s30, s3, s12
	s_addc_u32 s31, s15, s13
	s_and_b64 s[12:13], s[10:11], exec
	s_cselect_b32 s23, s31, s35
	s_cselect_b32 s84, s30, s34
	s_add_u32 s12, s26, 0x80080
	s_addc_u32 s13, s27, 0
	v_lshl_add_u64 v[132:133], s[12:13], 0, v[172:173]
	v_lshl_add_u64 v[134:135], s[12:13], 0, v[174:175]
	s_mov_b32 s85, -2
	s_mov_b64 s[12:13], 0
	s_and_b64 vcc, exec, s[20:21]
	s_cbranch_vccnz .Lsp_skip_1067
	s_setprio 1
.Lsp_skip_1067:
.LBB0_1067:
	s_add_u32 s34, s26, s12
	s_addc_u32 s35, s27, s13
	s_add_u32 s34, s34, 0x100
	s_addc_u32 s35, s35, 0
	s_add_u32 s83, s42, s12
	s_addc_u32 s92, s75, s13
	s_add_i32 s93, 0, 0x10000
	s_cmpk_eq_i32 s12, 0xf00
	s_cselect_b32 s37, s25, s35
	s_cselect_b32 s36, s81, s34
	s_cselect_b32 s35, s23, s92
	s_cselect_b32 s34, s84, s83
	s_add_i32 s83, 0, 0x14000
	v_add_u32_e32 v148, s93, v189
	v_add_u32_e32 v176, s83, v189
	ds_read_b128 v[136:139], v148
	ds_read_b128 v[140:143], v148 offset:1024
	ds_read_b128 v[144:147], v148 offset:2048
	ds_read_b128 v[148:151], v148 offset:3072
	ds_read_b128 v[152:155], v176
	ds_read_b128 v[156:159], v176 offset:1024
	ds_read_b128 v[160:163], v176 offset:2048
	ds_read_b128 v[176:179], v176 offset:3072
	v_lshl_add_u64 v[184:185], v[132:133], 0, s[12:13]
	s_add_i32 m0, s39, 0xc000
	ds_read_b128 v[180:183], v192
	ds_read_b128 v[194:197], v192 offset:1024
	ds_read_b128 v[198:201], v192 offset:2048
	ds_read_b128 v[202:205], v192 offset:3072
	ds_read_b128 v[206:209], v192 offset:4096
	ds_read_b128 v[210:213], v192 offset:5120
	ds_read_b128 v[214:217], v192 offset:6144
	ds_read_b128 v[226:229], v192 offset:7168
	global_load_lds_dwordx4 v[184:185], off
	v_lshl_add_u64 v[184:185], v[134:135], 0, s[12:13]
	s_add_i32 m0, s39, 0xe000
	s_nop 0
	global_load_lds_dwordx4 v[184:185], off
	s_waitcnt vmcnt(8)
	s_waitcnt lgkmcnt(0)
	s_barrier
	v_mfma_f32_16x16x32_bf16 v[8:11], v[136:139], v[180:183], v[8:11]
	v_mfma_f32_16x16x32_bf16 v[128:131], v[144:147], v[180:183], v[128:131]
	v_mfma_f32_16x16x32_bf16 v[124:127], v[136:139], v[198:201], v[124:127]
	v_mfma_f32_16x16x32_bf16 v[120:123], v[144:147], v[198:201], v[120:123]
	v_mfma_f32_16x16x32_bf16 v[116:119], v[136:139], v[206:209], v[116:119]
	v_mfma_f32_16x16x32_bf16 v[112:115], v[144:147], v[206:209], v[112:115]
	v_mfma_f32_16x16x32_bf16 v[108:111], v[136:139], v[214:217], v[108:111]
	v_mfma_f32_16x16x32_bf16 v[104:107], v[144:147], v[214:217], v[104:107]
	v_mfma_f32_16x16x32_bf16 v[8:11], v[140:143], v[194:197], v[8:11]
	v_mfma_f32_16x16x32_bf16 v[128:131], v[148:151], v[194:197], v[128:131]
	v_mfma_f32_16x16x32_bf16 v[124:127], v[140:143], v[202:205], v[124:127]
	v_mfma_f32_16x16x32_bf16 v[120:123], v[148:151], v[202:205], v[120:123]
	v_mfma_f32_16x16x32_bf16 v[116:119], v[140:143], v[210:213], v[116:119]
	v_mfma_f32_16x16x32_bf16 v[112:115], v[148:151], v[210:213], v[112:115]
	v_mfma_f32_16x16x32_bf16 v[108:111], v[140:143], v[226:229], v[108:111]
	v_mfma_f32_16x16x32_bf16 v[104:107], v[148:151], v[226:229], v[104:107]
	v_mfma_f32_16x16x32_bf16 v[100:103], v[152:155], v[180:183], v[100:103]
	v_mfma_f32_16x16x32_bf16 v[96:99], v[160:163], v[180:183], v[96:99]
	v_mfma_f32_16x16x32_bf16 v[92:95], v[152:155], v[198:201], v[92:95]
	v_mfma_f32_16x16x32_bf16 v[88:91], v[160:163], v[198:201], v[88:91]
	v_mfma_f32_16x16x32_bf16 v[84:87], v[152:155], v[206:209], v[84:87]
	v_mfma_f32_16x16x32_bf16 v[80:83], v[160:163], v[206:209], v[80:83]
	v_mfma_f32_16x16x32_bf16 v[76:79], v[152:155], v[214:217], v[76:79]
	v_mfma_f32_16x16x32_bf16 v[72:75], v[160:163], v[214:217], v[72:75]
	v_mfma_f32_16x16x32_bf16 v[100:103], v[156:159], v[194:197], v[100:103]
	v_mfma_f32_16x16x32_bf16 v[96:99], v[176:179], v[194:197], v[96:99]
	v_mfma_f32_16x16x32_bf16 v[92:95], v[156:159], v[202:205], v[92:95]
	v_mfma_f32_16x16x32_bf16 v[88:91], v[176:179], v[202:205], v[88:91]
	v_mfma_f32_16x16x32_bf16 v[84:87], v[156:159], v[210:213], v[84:87]
	v_mfma_f32_16x16x32_bf16 v[80:83], v[176:179], v[210:213], v[80:83]
	v_mfma_f32_16x16x32_bf16 v[76:79], v[156:159], v[226:229], v[76:79]
	v_mfma_f32_16x16x32_bf16 v[72:75], v[176:179], v[226:229], v[72:75]
	s_barrier
	s_add_i32 s92, s93, s38
	v_lshl_add_u64 v[184:185], s[34:35], 0, v[164:165]
	s_mov_b32 m0, s92
	ds_read_b128 v[180:183], v192 offset:16384
	ds_read_b128 v[194:197], v192 offset:17408
	ds_read_b128 v[198:201], v192 offset:18432
	ds_read_b128 v[202:205], v192 offset:19456
	ds_read_b128 v[206:209], v192 offset:20480
	ds_read_b128 v[210:213], v192 offset:21504
	ds_read_b128 v[214:217], v192 offset:22528
	ds_read_b128 v[226:229], v192 offset:23552
	global_load_lds_dwordx4 v[184:185], off
	s_add_i32 m0, s92, 0x2000
	s_add_u32 s92, s34, 0x80000
	v_lshl_add_u64 v[230:231], s[34:35], 0, v[168:169]
	s_addc_u32 s93, s35, 0
	s_add_i32 s83, s83, s38
	global_load_lds_dwordx4 v[230:231], off
	v_lshl_add_u64 v[232:233], s[92:93], 0, v[164:165]
	s_mov_b32 m0, s83
	v_lshl_add_u64 v[234:235], s[36:37], 0, v[166:167]
	global_load_lds_dwordx4 v[232:233], off
	v_lshl_add_u64 v[232:233], s[92:93], 0, v[168:169]
	s_add_i32 m0, s83, 0x2000
	s_nop 0
	global_load_lds_dwordx4 v[232:233], off
	v_lshl_add_u64 v[232:233], s[36:37], 0, v[0:1]
	s_mov_b32 m0, s39
	s_nop 0
	global_load_lds_dwordx4 v[232:233], off
	s_mov_b32 m0, s43
	s_nop 0
	global_load_lds_dwordx4 v[234:235], off
	s_waitcnt vmcnt(8)
	s_waitcnt lgkmcnt(0)
	s_barrier
	v_mfma_f32_16x16x32_bf16 v[68:71], v[136:139], v[180:183], v[68:71]
	v_mfma_f32_16x16x32_bf16 v[64:67], v[144:147], v[180:183], v[64:67]
	v_mfma_f32_16x16x32_bf16 v[60:63], v[136:139], v[198:201], v[60:63]
	v_mfma_f32_16x16x32_bf16 v[56:59], v[144:147], v[198:201], v[56:59]
	v_mfma_f32_16x16x32_bf16 v[52:55], v[136:139], v[206:209], v[52:55]
	v_mfma_f32_16x16x32_bf16 v[48:51], v[144:147], v[206:209], v[48:51]
	v_mfma_f32_16x16x32_bf16 v[44:47], v[136:139], v[214:217], v[44:47]
	v_mfma_f32_16x16x32_bf16 v[40:43], v[144:147], v[214:217], v[40:43]
	v_mfma_f32_16x16x32_bf16 v[68:71], v[140:143], v[194:197], v[68:71]
	v_mfma_f32_16x16x32_bf16 v[64:67], v[148:151], v[194:197], v[64:67]
	v_mfma_f32_16x16x32_bf16 v[60:63], v[140:143], v[202:205], v[60:63]
	v_mfma_f32_16x16x32_bf16 v[56:59], v[148:151], v[202:205], v[56:59]
	v_mfma_f32_16x16x32_bf16 v[52:55], v[140:143], v[210:213], v[52:55]
	v_mfma_f32_16x16x32_bf16 v[48:51], v[148:151], v[210:213], v[48:51]
	v_mfma_f32_16x16x32_bf16 v[44:47], v[140:143], v[226:229], v[44:47]
	v_mfma_f32_16x16x32_bf16 v[40:43], v[148:151], v[226:229], v[40:43]
	v_mfma_f32_16x16x32_bf16 v[36:39], v[152:155], v[180:183], v[36:39]
	v_mfma_f32_16x16x32_bf16 v[32:35], v[160:163], v[180:183], v[32:35]
	v_mfma_f32_16x16x32_bf16 v[28:31], v[152:155], v[198:201], v[28:31]
	v_mfma_f32_16x16x32_bf16 v[24:27], v[160:163], v[198:201], v[24:27]
	v_mfma_f32_16x16x32_bf16 v[20:23], v[152:155], v[206:209], v[20:23]
	v_mfma_f32_16x16x32_bf16 v[16:19], v[160:163], v[206:209], v[16:19]
	v_mfma_f32_16x16x32_bf16 v[12:15], v[152:155], v[214:217], v[12:15]
	v_mfma_f32_16x16x32_bf16 v[4:7], v[160:163], v[214:217], v[4:7]
	v_mfma_f32_16x16x32_bf16 v[36:39], v[156:159], v[194:197], v[36:39]
	v_mfma_f32_16x16x32_bf16 v[32:35], v[176:179], v[194:197], v[32:35]
	v_mfma_f32_16x16x32_bf16 v[28:31], v[156:159], v[202:205], v[28:31]
	v_mfma_f32_16x16x32_bf16 v[24:27], v[176:179], v[202:205], v[24:27]
	v_mfma_f32_16x16x32_bf16 v[20:23], v[156:159], v[210:213], v[20:23]
	v_mfma_f32_16x16x32_bf16 v[16:19], v[176:179], v[210:213], v[16:19]
	v_mfma_f32_16x16x32_bf16 v[12:15], v[156:159], v[226:229], v[12:15]
	v_mfma_f32_16x16x32_bf16 v[4:7], v[176:179], v[226:229], v[4:7]
	s_barrier
	s_add_i32 s83, 0, 0x18000
	s_add_i32 s92, 0, 0x1c000
	v_add_u32_e32 v148, s83, v189
	v_add_u32_e32 v176, s92, v189
	ds_read_b128 v[136:139], v148
	ds_read_b128 v[140:143], v148 offset:1024
	ds_read_b128 v[144:147], v148 offset:2048
	ds_read_b128 v[148:151], v148 offset:3072
	ds_read_b128 v[152:155], v176
	ds_read_b128 v[156:159], v176 offset:1024
	ds_read_b128 v[160:163], v176 offset:2048
	ds_read_b128 v[176:179], v176 offset:3072
	s_add_u32 s36, s36, 0x80000
	s_addc_u32 s37, s37, 0
	s_mov_b32 m0, s46
	v_lshl_add_u64 v[236:237], s[36:37], 0, v[0:1]
	ds_read_b128 v[180:183], v192 offset:32768
	ds_read_b128 v[194:197], v192 offset:33792
	ds_read_b128 v[198:201], v192 offset:34816
	ds_read_b128 v[202:205], v192 offset:35840
	ds_read_b128 v[206:209], v192 offset:36864
	ds_read_b128 v[210:213], v192 offset:37888
	ds_read_b128 v[214:217], v192 offset:38912
	ds_read_b128 v[226:229], v192 offset:39936
	global_load_lds_dwordx4 v[236:237], off
	v_lshl_add_u64 v[236:237], s[36:37], 0, v[166:167]
	s_mov_b32 m0, s47
	s_nop 0
	global_load_lds_dwordx4 v[236:237], off
	s_waitcnt vmcnt(8)
	s_waitcnt lgkmcnt(0)
	s_barrier
	v_mfma_f32_16x16x32_bf16 v[8:11], v[136:139], v[180:183], v[8:11]
	v_mfma_f32_16x16x32_bf16 v[128:131], v[144:147], v[180:183], v[128:131]
	v_mfma_f32_16x16x32_bf16 v[124:127], v[136:139], v[198:201], v[124:127]
	v_mfma_f32_16x16x32_bf16 v[120:123], v[144:147], v[198:201], v[120:123]
	v_mfma_f32_16x16x32_bf16 v[116:119], v[136:139], v[206:209], v[116:119]
	v_mfma_f32_16x16x32_bf16 v[112:115], v[144:147], v[206:209], v[112:115]
	v_mfma_f32_16x16x32_bf16 v[108:111], v[136:139], v[214:217], v[108:111]
	v_mfma_f32_16x16x32_bf16 v[104:107], v[144:147], v[214:217], v[104:107]
	v_mfma_f32_16x16x32_bf16 v[8:11], v[140:143], v[194:197], v[8:11]
	v_mfma_f32_16x16x32_bf16 v[128:131], v[148:151], v[194:197], v[128:131]
	v_mfma_f32_16x16x32_bf16 v[124:127], v[140:143], v[202:205], v[124:127]
	v_mfma_f32_16x16x32_bf16 v[120:123], v[148:151], v[202:205], v[120:123]
	v_mfma_f32_16x16x32_bf16 v[116:119], v[140:143], v[210:213], v[116:119]
	v_mfma_f32_16x16x32_bf16 v[112:115], v[148:151], v[210:213], v[112:115]
	v_mfma_f32_16x16x32_bf16 v[108:111], v[140:143], v[226:229], v[108:111]
	v_mfma_f32_16x16x32_bf16 v[104:107], v[148:151], v[226:229], v[104:107]
	v_mfma_f32_16x16x32_bf16 v[100:103], v[152:155], v[180:183], v[100:103]
	v_mfma_f32_16x16x32_bf16 v[96:99], v[160:163], v[180:183], v[96:99]
	v_mfma_f32_16x16x32_bf16 v[92:95], v[152:155], v[198:201], v[92:95]
	v_mfma_f32_16x16x32_bf16 v[88:91], v[160:163], v[198:201], v[88:91]
	v_mfma_f32_16x16x32_bf16 v[84:87], v[152:155], v[206:209], v[84:87]
	v_mfma_f32_16x16x32_bf16 v[80:83], v[160:163], v[206:209], v[80:83]
	v_mfma_f32_16x16x32_bf16 v[76:79], v[152:155], v[214:217], v[76:79]
	v_mfma_f32_16x16x32_bf16 v[72:75], v[160:163], v[214:217], v[72:75]
	v_mfma_f32_16x16x32_bf16 v[100:103], v[156:159], v[194:197], v[100:103]
	v_mfma_f32_16x16x32_bf16 v[96:99], v[176:179], v[194:197], v[96:99]
	v_mfma_f32_16x16x32_bf16 v[92:95], v[156:159], v[202:205], v[92:95]
	v_mfma_f32_16x16x32_bf16 v[88:91], v[176:179], v[202:205], v[88:91]
	v_mfma_f32_16x16x32_bf16 v[84:87], v[156:159], v[210:213], v[84:87]
	v_mfma_f32_16x16x32_bf16 v[80:83], v[176:179], v[210:213], v[80:83]
	v_mfma_f32_16x16x32_bf16 v[76:79], v[156:159], v[226:229], v[76:79]
	v_mfma_f32_16x16x32_bf16 v[72:75], v[176:179], v[226:229], v[72:75]
	s_barrier
	s_add_i32 s36, s83, s38
	v_lshl_add_u64 v[184:185], v[184:185], 0, s[70:71]
	s_mov_b32 m0, s36
	ds_read_b128 v[180:183], v192 offset:49152
	ds_read_b128 v[194:197], v192 offset:50176
	ds_read_b128 v[198:201], v192 offset:51200
	ds_read_b128 v[202:205], v192 offset:52224
	ds_read_b128 v[206:209], v192 offset:53248
	ds_read_b128 v[210:213], v192 offset:54272
	ds_read_b128 v[214:217], v192 offset:55296
	ds_read_b128 v[226:229], v192 offset:56320
	global_load_lds_dwordx4 v[184:185], off
	s_add_i32 m0, s36, 0x2000
	s_add_u32 s34, s34, 0x80080
	v_lshl_add_u64 v[184:185], v[230:231], 0, s[70:71]
	s_addc_u32 s35, s35, 0
	s_add_i32 s36, s92, s38
	global_load_lds_dwordx4 v[184:185], off
	v_lshl_add_u64 v[184:185], s[34:35], 0, v[164:165]
	s_mov_b32 m0, s36
	s_nop 0
	global_load_lds_dwordx4 v[184:185], off
	v_lshl_add_u64 v[184:185], s[34:35], 0, v[168:169]
	s_add_i32 m0, s36, 0x2000
	s_nop 0
	global_load_lds_dwordx4 v[184:185], off
	v_lshl_add_u64 v[184:185], v[232:233], 0, s[70:71]
	s_mov_b32 m0, s51
	s_nop 0
	global_load_lds_dwordx4 v[184:185], off
	v_lshl_add_u64 v[184:185], v[234:235], 0, s[70:71]
	s_mov_b32 m0, s52
	s_nop 0
	global_load_lds_dwordx4 v[184:185], off
	s_waitcnt vmcnt(8)
	s_waitcnt lgkmcnt(0)
	s_barrier
	v_mfma_f32_16x16x32_bf16 v[68:71], v[136:139], v[180:183], v[68:71]
	v_mfma_f32_16x16x32_bf16 v[64:67], v[144:147], v[180:183], v[64:67]
	v_mfma_f32_16x16x32_bf16 v[60:63], v[136:139], v[198:201], v[60:63]
	v_mfma_f32_16x16x32_bf16 v[56:59], v[144:147], v[198:201], v[56:59]
	v_mfma_f32_16x16x32_bf16 v[52:55], v[136:139], v[206:209], v[52:55]
	v_mfma_f32_16x16x32_bf16 v[48:51], v[144:147], v[206:209], v[48:51]
	v_mfma_f32_16x16x32_bf16 v[44:47], v[136:139], v[214:217], v[44:47]
	v_mfma_f32_16x16x32_bf16 v[40:43], v[144:147], v[214:217], v[40:43]
	v_mfma_f32_16x16x32_bf16 v[68:71], v[140:143], v[194:197], v[68:71]
	v_mfma_f32_16x16x32_bf16 v[64:67], v[148:151], v[194:197], v[64:67]
	v_mfma_f32_16x16x32_bf16 v[60:63], v[140:143], v[202:205], v[60:63]
	v_mfma_f32_16x16x32_bf16 v[56:59], v[148:151], v[202:205], v[56:59]
	v_mfma_f32_16x16x32_bf16 v[52:55], v[140:143], v[210:213], v[52:55]
	v_mfma_f32_16x16x32_bf16 v[48:51], v[148:151], v[210:213], v[48:51]
	v_mfma_f32_16x16x32_bf16 v[44:47], v[140:143], v[226:229], v[44:47]
	v_mfma_f32_16x16x32_bf16 v[40:43], v[148:151], v[226:229], v[40:43]
	v_mfma_f32_16x16x32_bf16 v[36:39], v[152:155], v[180:183], v[36:39]
	v_mfma_f32_16x16x32_bf16 v[32:35], v[160:163], v[180:183], v[32:35]
	v_mfma_f32_16x16x32_bf16 v[28:31], v[152:155], v[198:201], v[28:31]
	v_mfma_f32_16x16x32_bf16 v[24:27], v[160:163], v[198:201], v[24:27]
	v_mfma_f32_16x16x32_bf16 v[20:23], v[152:155], v[206:209], v[20:23]
	v_mfma_f32_16x16x32_bf16 v[16:19], v[160:163], v[206:209], v[16:19]
	v_mfma_f32_16x16x32_bf16 v[12:15], v[152:155], v[214:217], v[12:15]
	v_mfma_f32_16x16x32_bf16 v[4:7], v[160:163], v[214:217], v[4:7]
	v_mfma_f32_16x16x32_bf16 v[36:39], v[156:159], v[194:197], v[36:39]
	v_mfma_f32_16x16x32_bf16 v[32:35], v[176:179], v[194:197], v[32:35]
	v_mfma_f32_16x16x32_bf16 v[28:31], v[156:159], v[202:205], v[28:31]
	v_mfma_f32_16x16x32_bf16 v[24:27], v[176:179], v[202:205], v[24:27]
	v_mfma_f32_16x16x32_bf16 v[20:23], v[156:159], v[210:213], v[20:23]
	v_mfma_f32_16x16x32_bf16 v[16:19], v[176:179], v[210:213], v[16:19]
	v_mfma_f32_16x16x32_bf16 v[12:15], v[156:159], v[226:229], v[12:15]
	v_mfma_f32_16x16x32_bf16 v[4:7], v[176:179], v[226:229], v[4:7]
	s_barrier
	s_add_i32 s85, s85, 2
	s_add_u32 s12, s12, 0x100
	s_addc_u32 s13, s13, 0
	s_cmp_gt_u32 s85, 29
	s_cbranch_scc0 .LBB0_1067
	s_and_b64 vcc, exec, s[20:21]
	s_cbranch_vccz .LBB0_1070
	s_barrier
.LBB0_1070:
	s_setprio 0
	v_add_u32_e32 v193, s54, v188
	ds_read2_b32 v[184:185], v193 offset1:16
	ds_read2_b32 v[182:183], v193 offset0:32 offset1:48
	ds_read2_b32 v[178:179], v193 offset0:64 offset1:80
	ds_read2_b32 v[176:177], v193 offset0:96 offset1:112
	s_waitcnt lgkmcnt(0)
	v_readlane_b32 s12, v254, 11
	v_readlane_b32 s13, v254, 12
	v_and_b32_e32 v180, 15, v219
	v_bfe_u32 v181, v219, 4, 2
	v_bfe_u32 v234, v219, 6, 2
	v_bfe_u32 v235, v219, 8, 1
	v_lshlrev_b32_e32 v236, 5, v234
	v_lshl_or_b32 v236, v181, 3, v236
	s_load_dwordx2 s[34:35], s[12:13], 0x88
	s_load_dwordx2 s[36:37], s[12:13], 0x90
	s_lshl_b32 s23, s67, 7
	v_or_b32_e32 v237, s23, v236
	v_lshlrev_b32_e32 v237, 2, v237
	v_lshlrev_b32_e32 v234, 10, v180
	v_lshl_add_u32 v234, v236, 2, v234
	v_lshl_add_u32 v234, v235, 11, v234
	v_add_u32_e32 v234, 0x1c800, v234
	v_lshl_or_b32 v245, v235, 6, v180
	s_lshl_b32 s23, s66, 8
	v_or_b32_e32 v245, s23, v245
	v_mul_u32_u24_e32 v245, 0x2c00, v245
	v_lshrrev_b32_e32 v221, 1, v237
	v_add_u32_e32 v245, v245, v221
	v_mul_u32_u24_e32 v181, 12, v235
	v_sub_u32_e32 v181, v180, v181
	v_add_u32_e32 v181, 2, v181
	s_lshl_b32 s23, s66, 2
	v_add_u32_e32 v181, s23, v181
	v_mul_u32_u24_e32 v181, 0x2c00, v181
	s_lshl_b32 s25, s67, 8
	v_add3_u32 v181, v181, s25, v236
	v_lshlrev_b32_e32 v181, 2, v181
	s_waitcnt lgkmcnt(0)
	s_mul_i32 s23, s68, 0x21000
	s_add_u32 s34, s34, s23
	s_addc_u32 s35, s35, 0
	s_mul_i32 s23, s68, 0xb000
	s_add_u32 s36, s36, s23
	s_addc_u32 s37, s37, 0
	v_add_u32_e32 v221, 0x16000, v237
	global_load_dwordx4 v[132:135], v221, s[34:35]
	global_load_dwordx4 v[136:139], v221, s[34:35] offset:16
	v_add_u32_e32 v240, 0xb000, v237
	global_load_dwordx4 v[140:143], v240, s[34:35]
	global_load_dwordx4 v[144:147], v240, s[34:35] offset:16
	global_load_dwordx4 v[148:151], v237, s[34:35]
	global_load_dwordx4 v[152:155], v237, s[34:35] offset:16
	global_load_dwordx4 v[156:159], v237, s[36:37]
	global_load_dwordx4 v[160:163], v237, s[36:37] offset:16
	v_add_u32_e32 v221, 0x1b800, v237
	global_load_dwordx4 v[194:197], v221, s[34:35]
	global_load_dwordx4 v[198:201], v221, s[34:35] offset:16
	v_add_u32_e32 v240, 0x10800, v237
	global_load_dwordx4 v[202:205], v240, s[34:35]
	global_load_dwordx4 v[206:209], v240, s[34:35] offset:16
	v_add_u32_e32 v221, 0x5800, v237
	global_load_dwordx4 v[210:213], v221, s[34:35]
	global_load_dwordx4 v[214:217], v221, s[34:35] offset:16
	v_add_u32_e32 v240, 0x5800, v237
	global_load_dwordx4 v[226:229], v240, s[36:37]
	global_load_dwordx4 v[230:233], v240, s[36:37] offset:16
	s_add_u32 s12, s18, 0x16000000
	s_addc_u32 s13, s19, 0
	v_pk_mul_f32 v[8:9], v[8:9], v[184:185] op_sel_hi:[1,0]
	v_pk_mul_f32 v[10:11], v[10:11], v[184:185] op_sel_hi:[1,0]
	v_pk_mul_f32 v[128:129], v[128:129], v[184:185] op_sel_hi:[1,0]
	v_pk_mul_f32 v[130:131], v[130:131], v[184:185] op_sel_hi:[1,0]
	v_pk_mul_f32 v[100:101], v[100:101], v[184:185] op_sel_hi:[1,0]
	v_pk_mul_f32 v[102:103], v[102:103], v[184:185] op_sel_hi:[1,0]
	v_pk_mul_f32 v[96:97], v[96:97], v[184:185] op_sel_hi:[1,0]
	v_pk_mul_f32 v[98:99], v[98:99], v[184:185] op_sel_hi:[1,0]
	v_pk_mul_f32 v[124:125], v[124:125], v[184:185] op_sel:[0,1] op_sel_hi:[1,1]
	v_pk_mul_f32 v[126:127], v[126:127], v[184:185] op_sel:[0,1] op_sel_hi:[1,1]
	v_pk_mul_f32 v[120:121], v[120:121], v[184:185] op_sel:[0,1] op_sel_hi:[1,1]
	v_pk_mul_f32 v[122:123], v[122:123], v[184:185] op_sel:[0,1] op_sel_hi:[1,1]
	v_pk_mul_f32 v[92:93], v[92:93], v[184:185] op_sel:[0,1] op_sel_hi:[1,1]
	v_pk_mul_f32 v[94:95], v[94:95], v[184:185] op_sel:[0,1] op_sel_hi:[1,1]
	v_pk_mul_f32 v[88:89], v[88:89], v[184:185] op_sel:[0,1] op_sel_hi:[1,1]
	v_pk_mul_f32 v[90:91], v[90:91], v[184:185] op_sel:[0,1] op_sel_hi:[1,1]
	v_pk_mul_f32 v[116:117], v[116:117], v[182:183] op_sel_hi:[1,0]
	v_pk_mul_f32 v[118:119], v[118:119], v[182:183] op_sel_hi:[1,0]
	v_pk_mul_f32 v[112:113], v[112:113], v[182:183] op_sel_hi:[1,0]
	v_pk_mul_f32 v[114:115], v[114:115], v[182:183] op_sel_hi:[1,0]
	v_pk_mul_f32 v[84:85], v[84:85], v[182:183] op_sel_hi:[1,0]
	v_pk_mul_f32 v[86:87], v[86:87], v[182:183] op_sel_hi:[1,0]
	v_pk_mul_f32 v[80:81], v[80:81], v[182:183] op_sel_hi:[1,0]
	v_pk_mul_f32 v[82:83], v[82:83], v[182:183] op_sel_hi:[1,0]
	v_pk_mul_f32 v[108:109], v[108:109], v[182:183] op_sel:[0,1] op_sel_hi:[1,1]
	v_pk_mul_f32 v[110:111], v[110:111], v[182:183] op_sel:[0,1] op_sel_hi:[1,1]
	v_pk_mul_f32 v[104:105], v[104:105], v[182:183] op_sel:[0,1] op_sel_hi:[1,1]
	v_pk_mul_f32 v[106:107], v[106:107], v[182:183] op_sel:[0,1] op_sel_hi:[1,1]
	v_pk_mul_f32 v[76:77], v[76:77], v[182:183] op_sel:[0,1] op_sel_hi:[1,1]
	v_pk_mul_f32 v[78:79], v[78:79], v[182:183] op_sel:[0,1] op_sel_hi:[1,1]
	v_pk_mul_f32 v[72:73], v[72:73], v[182:183] op_sel:[0,1] op_sel_hi:[1,1]
	v_pk_mul_f32 v[74:75], v[74:75], v[182:183] op_sel:[0,1] op_sel_hi:[1,1]
	v_pk_mul_f32 v[68:69], v[68:69], v[178:179] op_sel_hi:[1,0]
	v_pk_mul_f32 v[70:71], v[70:71], v[178:179] op_sel_hi:[1,0]
	v_pk_mul_f32 v[64:65], v[64:65], v[178:179] op_sel_hi:[1,0]
	v_pk_mul_f32 v[66:67], v[66:67], v[178:179] op_sel_hi:[1,0]
	v_pk_mul_f32 v[36:37], v[36:37], v[178:179] op_sel_hi:[1,0]
	v_pk_mul_f32 v[38:39], v[38:39], v[178:179] op_sel_hi:[1,0]
	v_pk_mul_f32 v[32:33], v[32:33], v[178:179] op_sel_hi:[1,0]
	v_pk_mul_f32 v[34:35], v[34:35], v[178:179] op_sel_hi:[1,0]
	v_pk_mul_f32 v[60:61], v[60:61], v[178:179] op_sel:[0,1] op_sel_hi:[1,1]
	v_pk_mul_f32 v[62:63], v[62:63], v[178:179] op_sel:[0,1] op_sel_hi:[1,1]
	v_pk_mul_f32 v[56:57], v[56:57], v[178:179] op_sel:[0,1] op_sel_hi:[1,1]
	v_pk_mul_f32 v[58:59], v[58:59], v[178:179] op_sel:[0,1] op_sel_hi:[1,1]
	v_pk_mul_f32 v[28:29], v[28:29], v[178:179] op_sel:[0,1] op_sel_hi:[1,1]
	v_pk_mul_f32 v[30:31], v[30:31], v[178:179] op_sel:[0,1] op_sel_hi:[1,1]
	v_pk_mul_f32 v[24:25], v[24:25], v[178:179] op_sel:[0,1] op_sel_hi:[1,1]
	v_pk_mul_f32 v[26:27], v[26:27], v[178:179] op_sel:[0,1] op_sel_hi:[1,1]
	v_pk_mul_f32 v[52:53], v[52:53], v[176:177] op_sel_hi:[1,0]
	v_pk_mul_f32 v[54:55], v[54:55], v[176:177] op_sel_hi:[1,0]
	v_pk_mul_f32 v[48:49], v[48:49], v[176:177] op_sel_hi:[1,0]
	v_pk_mul_f32 v[50:51], v[50:51], v[176:177] op_sel_hi:[1,0]
	v_pk_mul_f32 v[20:21], v[20:21], v[176:177] op_sel_hi:[1,0]
	v_pk_mul_f32 v[22:23], v[22:23], v[176:177] op_sel_hi:[1,0]
	v_pk_mul_f32 v[16:17], v[16:17], v[176:177] op_sel_hi:[1,0]
	v_pk_mul_f32 v[18:19], v[18:19], v[176:177] op_sel_hi:[1,0]
	v_pk_mul_f32 v[44:45], v[44:45], v[176:177] op_sel:[0,1] op_sel_hi:[1,1]
	v_pk_mul_f32 v[46:47], v[46:47], v[176:177] op_sel:[0,1] op_sel_hi:[1,1]
	v_pk_mul_f32 v[40:41], v[40:41], v[176:177] op_sel:[0,1] op_sel_hi:[1,1]
	v_pk_mul_f32 v[42:43], v[42:43], v[176:177] op_sel:[0,1] op_sel_hi:[1,1]
	v_pk_mul_f32 v[12:13], v[12:13], v[176:177] op_sel:[0,1] op_sel_hi:[1,1]
	v_pk_mul_f32 v[14:15], v[14:15], v[176:177] op_sel:[0,1] op_sel_hi:[1,1]
	v_pk_mul_f32 v[4:5], v[4:5], v[176:177] op_sel:[0,1] op_sel_hi:[1,1]
	v_pk_mul_f32 v[6:7], v[6:7], v[176:177] op_sel:[0,1] op_sel_hi:[1,1]
	s_mov_b32 exec_lo, 0xc000c000
	s_mov_b32 exec_hi, 0xc000c000
	ds_write_b128 v234, v[108:111] offset:2048
	ds_write_b128 v234, v[104:107] offset:2064
	ds_write_b128 v234, v[76:79] offset:2560
	ds_write_b128 v234, v[72:75] offset:2576
	s_and_b64 vcc, exec, s[16:17]
	s_cbranch_vccnz .Lfe_wr1
	ds_write_b128 v234, v[44:47] offset:6144
	ds_write_b128 v234, v[40:43] offset:6160
	ds_write_b128 v234, v[12:15] offset:6656
	ds_write_b128 v234, v[4:7] offset:6672
	v_mov_b32_e32 v246, 0
	v_mov_b32_e32 v247, 0
	v_mov_b32_e32 v248, 0
	v_mov_b32_e32 v249, 0
	s_nop 1
	ds_write_b128 v234, v[246:249] offset:0
	ds_write_b128 v234, v[246:249] offset:16
	ds_write_b128 v234, v[246:249] offset:512
	ds_write_b128 v234, v[246:249] offset:528
	s_mov_b32 exec_lo, 0x30003
	s_mov_b32 exec_hi, 0x30003
	global_store_dwordx4 v181, v[8:11], s[18:19]
	global_store_dwordx4 v181, v[128:131], s[18:19] offset:16
	global_store_dwordx4 v181, v[100:103], s[18:19] offset:512
	global_store_dwordx4 v181, v[96:99], s[18:19] offset:528
	s_branch .Lfe_join

.LBB0_1204:
	s_add_u32 s52, s24, 0x100
	v_mov_b32_e32 v4, 0
	s_addc_u32 s54, s25, 0
	s_mov_b32 s66, -2
	s_waitcnt lgkmcnt(0)
	v_mov_b32_e32 v5, v4
	v_mov_b32_e32 v6, v4
	v_mov_b32_e32 v7, v4
	v_mov_b32_e32 v8, v4
	v_mov_b32_e32 v9, v4
	v_mov_b32_e32 v10, v4
	v_mov_b32_e32 v11, v4
	v_mov_b32_e32 v20, v4
	v_mov_b32_e32 v21, v4
	v_mov_b32_e32 v22, v4
	v_mov_b32_e32 v23, v4
	v_mov_b32_e32 v24, v4
	v_mov_b32_e32 v25, v4
	v_mov_b32_e32 v26, v4
	v_mov_b32_e32 v27, v4
	v_mov_b32_e32 v36, v4
	v_mov_b32_e32 v37, v4
	v_mov_b32_e32 v38, v4
	v_mov_b32_e32 v39, v4
	v_mov_b32_e32 v40, v4
	v_mov_b32_e32 v41, v4
	v_mov_b32_e32 v42, v4
	v_mov_b32_e32 v43, v4
	v_mov_b32_e32 v52, v4
	v_mov_b32_e32 v53, v4
	v_mov_b32_e32 v54, v4
	v_mov_b32_e32 v55, v4
	v_mov_b32_e32 v56, v4
	v_mov_b32_e32 v57, v4
	v_mov_b32_e32 v58, v4
	v_mov_b32_e32 v59, v4
	v_mov_b32_e32 v12, v4
	v_mov_b32_e32 v13, v4
	v_mov_b32_e32 v14, v4
	v_mov_b32_e32 v15, v4
	v_mov_b32_e32 v16, v4
	v_mov_b32_e32 v17, v4
	v_mov_b32_e32 v18, v4
	v_mov_b32_e32 v19, v4
	v_mov_b32_e32 v28, v4
	v_mov_b32_e32 v29, v4
	v_mov_b32_e32 v30, v4
	v_mov_b32_e32 v31, v4
	v_mov_b32_e32 v32, v4
	v_mov_b32_e32 v33, v4
	v_mov_b32_e32 v34, v4
	v_mov_b32_e32 v35, v4
	v_mov_b32_e32 v44, v4
	v_mov_b32_e32 v45, v4
	v_mov_b32_e32 v46, v4
	v_mov_b32_e32 v47, v4
	v_mov_b32_e32 v48, v4
	v_mov_b32_e32 v49, v4
	v_mov_b32_e32 v50, v4
	v_mov_b32_e32 v51, v4
	v_mov_b32_e32 v60, v4
	v_mov_b32_e32 v61, v4
	v_mov_b32_e32 v62, v4
	v_mov_b32_e32 v63, v4
	v_mov_b32_e32 v64, v4
	v_mov_b32_e32 v65, v4
	v_mov_b32_e32 v66, v4
	v_mov_b32_e32 v67, v4
	v_mov_b32_e32 v68, v4
	v_mov_b32_e32 v69, v4
	v_mov_b32_e32 v70, v4
	v_mov_b32_e32 v71, v4
	v_mov_b32_e32 v72, v4
	v_mov_b32_e32 v73, v4
	v_mov_b32_e32 v74, v4
	v_mov_b32_e32 v75, v4
	v_mov_b32_e32 v84, v4
	v_mov_b32_e32 v85, v4
	v_mov_b32_e32 v86, v4
	v_mov_b32_e32 v87, v4
	v_mov_b32_e32 v88, v4
	v_mov_b32_e32 v89, v4
	v_mov_b32_e32 v90, v4
	v_mov_b32_e32 v91, v4
	v_mov_b32_e32 v100, v4
	v_mov_b32_e32 v101, v4
	v_mov_b32_e32 v102, v4
	v_mov_b32_e32 v103, v4
	v_mov_b32_e32 v104, v4
	v_mov_b32_e32 v105, v4
	v_mov_b32_e32 v106, v4
	v_mov_b32_e32 v107, v4
	v_mov_b32_e32 v116, v4
	v_mov_b32_e32 v117, v4
	v_mov_b32_e32 v118, v4
	v_mov_b32_e32 v119, v4
	v_mov_b32_e32 v120, v4
	v_mov_b32_e32 v121, v4
	v_mov_b32_e32 v122, v4
	v_mov_b32_e32 v123, v4
	v_mov_b32_e32 v76, v4
	v_mov_b32_e32 v77, v4
	v_mov_b32_e32 v78, v4
	v_mov_b32_e32 v79, v4
	v_mov_b32_e32 v80, v4
	v_mov_b32_e32 v81, v4
	v_mov_b32_e32 v82, v4
	v_mov_b32_e32 v83, v4
	v_mov_b32_e32 v92, v4
	v_mov_b32_e32 v93, v4
	v_mov_b32_e32 v94, v4
	v_mov_b32_e32 v95, v4
	v_mov_b32_e32 v96, v4
	v_mov_b32_e32 v97, v4
	v_mov_b32_e32 v98, v4
	v_mov_b32_e32 v99, v4
	v_mov_b32_e32 v108, v4
	v_mov_b32_e32 v109, v4
	v_mov_b32_e32 v110, v4
	v_mov_b32_e32 v111, v4
	v_mov_b32_e32 v112, v4
	v_mov_b32_e32 v113, v4
	v_mov_b32_e32 v114, v4
	v_mov_b32_e32 v115, v4
	v_mov_b32_e32 v124, v4
	v_mov_b32_e32 v125, v4
	v_mov_b32_e32 v126, v4
	v_mov_b32_e32 v127, v4
	v_mov_b32_e32 v128, v4
	v_mov_b32_e32 v129, v4
	v_mov_b32_e32 v130, v4
	v_mov_b32_e32 v131, v4
	s_and_b64 vcc, exec, s[18:19]
	s_cbranch_vccnz .Lsp_skip_1205
	s_setprio 1
.Lsp_skip_1205:
.LBB0_1205:
	s_add_u32 s24, s22, 0x100
	s_addc_u32 s25, s23, 0
	s_add_i32 s67, 0, 0x10000
	s_cmpk_eq_i32 s66, 0x54
	s_cselect_b32 s29, s9, s25
	s_cselect_b32 s28, s8, s24
	s_cselect_b32 s27, s21, s54
	s_cselect_b32 s26, s20, s52
	s_add_i32 s69, 0, 0x14000
	v_add_u32_e32 v144, s67, v182
	v_add_u32_e32 v170, s69, v182
	ds_read_b128 v[132:135], v144
	ds_read_b128 v[136:139], v144 offset:1024
	ds_read_b128 v[140:143], v144 offset:2048
	ds_read_b128 v[144:147], v144 offset:3072
	ds_read_b128 v[148:151], v170
	ds_read_b128 v[152:155], v170 offset:1024
	ds_read_b128 v[156:159], v170 offset:2048
	ds_read_b128 v[170:173], v170 offset:3072
	v_lshl_add_u64 v[212:213], s[22:23], 0, v[166:167]
	s_add_i32 m0, s31, 0xc000
	ds_read_b128 v[174:177], v186
	ds_read_b128 v[178:181], v186 offset:1024
	ds_read_b128 v[188:191], v186 offset:2048
	ds_read_b128 v[192:195], v186 offset:3072
	ds_read_b128 v[196:199], v186 offset:4096
	ds_read_b128 v[200:203], v186 offset:5120
	ds_read_b128 v[204:207], v186 offset:6144
	ds_read_b128 v[208:211], v186 offset:7168
	global_load_lds_dwordx4 v[212:213], off
	v_lshl_add_u64 v[212:213], s[22:23], 0, v[168:169]
	s_add_i32 m0, s31, 0xe000
	s_nop 0
	global_load_lds_dwordx4 v[212:213], off
	s_waitcnt vmcnt(8)
	s_waitcnt lgkmcnt(0)
	s_barrier
	v_mfma_f32_16x16x32_bf16 v[128:131], v[132:135], v[174:177], v[128:131]
	v_mfma_f32_16x16x32_bf16 v[124:127], v[140:143], v[174:177], v[124:127]
	v_mfma_f32_16x16x32_bf16 v[112:115], v[132:135], v[188:191], v[112:115]
	v_mfma_f32_16x16x32_bf16 v[108:111], v[140:143], v[188:191], v[108:111]
	v_mfma_f32_16x16x32_bf16 v[96:99], v[132:135], v[196:199], v[96:99]
	v_mfma_f32_16x16x32_bf16 v[92:95], v[140:143], v[196:199], v[92:95]
	v_mfma_f32_16x16x32_bf16 v[80:83], v[132:135], v[204:207], v[80:83]
	v_mfma_f32_16x16x32_bf16 v[76:79], v[140:143], v[204:207], v[76:79]
	v_mfma_f32_16x16x32_bf16 v[128:131], v[136:139], v[178:181], v[128:131]
	v_mfma_f32_16x16x32_bf16 v[124:127], v[144:147], v[178:181], v[124:127]
	v_mfma_f32_16x16x32_bf16 v[112:115], v[136:139], v[192:195], v[112:115]
	v_mfma_f32_16x16x32_bf16 v[108:111], v[144:147], v[192:195], v[108:111]
	v_mfma_f32_16x16x32_bf16 v[96:99], v[136:139], v[200:203], v[96:99]
	v_mfma_f32_16x16x32_bf16 v[92:95], v[144:147], v[200:203], v[92:95]
	v_mfma_f32_16x16x32_bf16 v[80:83], v[136:139], v[208:211], v[80:83]
	v_mfma_f32_16x16x32_bf16 v[76:79], v[144:147], v[208:211], v[76:79]
	v_mfma_f32_16x16x32_bf16 v[120:123], v[148:151], v[174:177], v[120:123]
	v_mfma_f32_16x16x32_bf16 v[116:119], v[156:159], v[174:177], v[116:119]
	v_mfma_f32_16x16x32_bf16 v[104:107], v[148:151], v[188:191], v[104:107]
	v_mfma_f32_16x16x32_bf16 v[100:103], v[156:159], v[188:191], v[100:103]
	v_mfma_f32_16x16x32_bf16 v[88:91], v[148:151], v[196:199], v[88:91]
	v_mfma_f32_16x16x32_bf16 v[84:87], v[156:159], v[196:199], v[84:87]
	v_mfma_f32_16x16x32_bf16 v[72:75], v[148:151], v[204:207], v[72:75]
	v_mfma_f32_16x16x32_bf16 v[68:71], v[156:159], v[204:207], v[68:71]
	v_mfma_f32_16x16x32_bf16 v[120:123], v[152:155], v[178:181], v[120:123]
	v_mfma_f32_16x16x32_bf16 v[116:119], v[170:173], v[178:181], v[116:119]
	v_mfma_f32_16x16x32_bf16 v[104:107], v[152:155], v[192:195], v[104:107]
	v_mfma_f32_16x16x32_bf16 v[100:103], v[170:173], v[192:195], v[100:103]
	v_mfma_f32_16x16x32_bf16 v[88:91], v[152:155], v[200:203], v[88:91]
	v_mfma_f32_16x16x32_bf16 v[84:87], v[170:173], v[200:203], v[84:87]
	v_mfma_f32_16x16x32_bf16 v[72:75], v[152:155], v[208:211], v[72:75]
	v_mfma_f32_16x16x32_bf16 v[68:71], v[170:173], v[208:211], v[68:71]
	s_barrier
	s_add_i32 s22, s67, s30
	v_lshl_add_u64 v[212:213], s[26:27], 0, v[162:163]
	s_mov_b32 m0, s22
	ds_read_b128 v[174:177], v186 offset:16384
	ds_read_b128 v[178:181], v186 offset:17408
	ds_read_b128 v[188:191], v186 offset:18432
	ds_read_b128 v[192:195], v186 offset:19456
	ds_read_b128 v[196:199], v186 offset:20480
	ds_read_b128 v[200:203], v186 offset:21504
	ds_read_b128 v[204:207], v186 offset:22528
	ds_read_b128 v[208:211], v186 offset:23552
	global_load_lds_dwordx4 v[212:213], off
	s_add_i32 m0, s22, 0x2000
	s_add_u32 s22, s26, 0x160000
	v_lshl_add_u64 v[214:215], s[26:27], 0, v[0:1]
	s_addc_u32 s23, s27, 0
	s_add_i32 s67, s69, s30
	global_load_lds_dwordx4 v[214:215], off
	v_lshl_add_u64 v[216:217], s[22:23], 0, v[162:163]
	s_mov_b32 m0, s67
	v_lshl_add_u64 v[226:227], s[28:29], 0, v[160:161]
	global_load_lds_dwordx4 v[216:217], off
	v_lshl_add_u64 v[216:217], s[22:23], 0, v[0:1]
	s_add_i32 m0, s67, 0x2000
	s_nop 0
	global_load_lds_dwordx4 v[216:217], off
	v_lshl_add_u64 v[216:217], s[28:29], 0, v[164:165]
	s_mov_b32 m0, s31
	s_nop 0
	global_load_lds_dwordx4 v[216:217], off
	s_mov_b32 m0, s34
	s_nop 0
	global_load_lds_dwordx4 v[226:227], off
	s_waitcnt vmcnt(8)
	s_waitcnt lgkmcnt(0)
	s_barrier
	v_mfma_f32_16x16x32_bf16 v[64:67], v[132:135], v[174:177], v[64:67]
	v_mfma_f32_16x16x32_bf16 v[60:63], v[140:143], v[174:177], v[60:63]
	v_mfma_f32_16x16x32_bf16 v[48:51], v[132:135], v[188:191], v[48:51]
	v_mfma_f32_16x16x32_bf16 v[44:47], v[140:143], v[188:191], v[44:47]
	v_mfma_f32_16x16x32_bf16 v[32:35], v[132:135], v[196:199], v[32:35]
	v_mfma_f32_16x16x32_bf16 v[28:31], v[140:143], v[196:199], v[28:31]
	v_mfma_f32_16x16x32_bf16 v[16:19], v[132:135], v[204:207], v[16:19]
	v_mfma_f32_16x16x32_bf16 v[12:15], v[140:143], v[204:207], v[12:15]
	v_mfma_f32_16x16x32_bf16 v[64:67], v[136:139], v[178:181], v[64:67]
	v_mfma_f32_16x16x32_bf16 v[60:63], v[144:147], v[178:181], v[60:63]
	v_mfma_f32_16x16x32_bf16 v[48:51], v[136:139], v[192:195], v[48:51]
	v_mfma_f32_16x16x32_bf16 v[44:47], v[144:147], v[192:195], v[44:47]
	v_mfma_f32_16x16x32_bf16 v[32:35], v[136:139], v[200:203], v[32:35]
	v_mfma_f32_16x16x32_bf16 v[28:31], v[144:147], v[200:203], v[28:31]
	v_mfma_f32_16x16x32_bf16 v[16:19], v[136:139], v[208:211], v[16:19]
	v_mfma_f32_16x16x32_bf16 v[12:15], v[144:147], v[208:211], v[12:15]
	v_mfma_f32_16x16x32_bf16 v[56:59], v[148:151], v[174:177], v[56:59]
	v_mfma_f32_16x16x32_bf16 v[52:55], v[156:159], v[174:177], v[52:55]
	v_mfma_f32_16x16x32_bf16 v[40:43], v[148:151], v[188:191], v[40:43]
	v_mfma_f32_16x16x32_bf16 v[36:39], v[156:159], v[188:191], v[36:39]
	v_mfma_f32_16x16x32_bf16 v[24:27], v[148:151], v[196:199], v[24:27]
	v_mfma_f32_16x16x32_bf16 v[20:23], v[156:159], v[196:199], v[20:23]
	v_mfma_f32_16x16x32_bf16 v[8:11], v[148:151], v[204:207], v[8:11]
	v_mfma_f32_16x16x32_bf16 v[4:7], v[156:159], v[204:207], v[4:7]
	v_mfma_f32_16x16x32_bf16 v[56:59], v[152:155], v[178:181], v[56:59]
	v_mfma_f32_16x16x32_bf16 v[52:55], v[170:173], v[178:181], v[52:55]
	v_mfma_f32_16x16x32_bf16 v[40:43], v[152:155], v[192:195], v[40:43]
	v_mfma_f32_16x16x32_bf16 v[36:39], v[170:173], v[192:195], v[36:39]
	v_mfma_f32_16x16x32_bf16 v[24:27], v[152:155], v[200:203], v[24:27]
	v_mfma_f32_16x16x32_bf16 v[20:23], v[170:173], v[200:203], v[20:23]
	v_mfma_f32_16x16x32_bf16 v[8:11], v[152:155], v[208:211], v[8:11]
	v_mfma_f32_16x16x32_bf16 v[4:7], v[170:173], v[208:211], v[4:7]
	s_barrier
	s_add_i32 s67, 0, 0x18000
	s_add_i32 s69, 0, 0x1c000
	v_add_u32_e32 v144, s67, v182
	v_add_u32_e32 v170, s69, v182
	ds_read_b128 v[132:135], v144
	ds_read_b128 v[136:139], v144 offset:1024
	ds_read_b128 v[140:143], v144 offset:2048
	ds_read_b128 v[144:147], v144 offset:3072
	ds_read_b128 v[148:151], v170
	ds_read_b128 v[152:155], v170 offset:1024
	ds_read_b128 v[156:159], v170 offset:2048
	ds_read_b128 v[170:173], v170 offset:3072
	s_add_u32 s22, s28, 0x160000
	s_addc_u32 s23, s29, 0
	s_mov_b32 m0, s35
	v_lshl_add_u64 v[228:229], s[22:23], 0, v[164:165]
	ds_read_b128 v[174:177], v186 offset:32768
	ds_read_b128 v[178:181], v186 offset:33792
	ds_read_b128 v[188:191], v186 offset:34816
	ds_read_b128 v[192:195], v186 offset:35840
	ds_read_b128 v[196:199], v186 offset:36864
	ds_read_b128 v[200:203], v186 offset:37888
	ds_read_b128 v[204:207], v186 offset:38912
	ds_read_b128 v[208:211], v186 offset:39936
	global_load_lds_dwordx4 v[228:229], off
	v_lshl_add_u64 v[228:229], s[22:23], 0, v[160:161]
	s_mov_b32 m0, s36
	s_nop 0
	global_load_lds_dwordx4 v[228:229], off
	s_waitcnt vmcnt(8)
	s_waitcnt lgkmcnt(0)
	s_barrier
	v_mfma_f32_16x16x32_bf16 v[128:131], v[132:135], v[174:177], v[128:131]
	v_mfma_f32_16x16x32_bf16 v[124:127], v[140:143], v[174:177], v[124:127]
	v_mfma_f32_16x16x32_bf16 v[112:115], v[132:135], v[188:191], v[112:115]
	v_mfma_f32_16x16x32_bf16 v[108:111], v[140:143], v[188:191], v[108:111]
	v_mfma_f32_16x16x32_bf16 v[96:99], v[132:135], v[196:199], v[96:99]
	v_mfma_f32_16x16x32_bf16 v[92:95], v[140:143], v[196:199], v[92:95]
	v_mfma_f32_16x16x32_bf16 v[80:83], v[132:135], v[204:207], v[80:83]
	v_mfma_f32_16x16x32_bf16 v[76:79], v[140:143], v[204:207], v[76:79]
	v_mfma_f32_16x16x32_bf16 v[128:131], v[136:139], v[178:181], v[128:131]
	v_mfma_f32_16x16x32_bf16 v[124:127], v[144:147], v[178:181], v[124:127]
	v_mfma_f32_16x16x32_bf16 v[112:115], v[136:139], v[192:195], v[112:115]
	v_mfma_f32_16x16x32_bf16 v[108:111], v[144:147], v[192:195], v[108:111]
	v_mfma_f32_16x16x32_bf16 v[96:99], v[136:139], v[200:203], v[96:99]
	v_mfma_f32_16x16x32_bf16 v[92:95], v[144:147], v[200:203], v[92:95]
	v_mfma_f32_16x16x32_bf16 v[80:83], v[136:139], v[208:211], v[80:83]
	v_mfma_f32_16x16x32_bf16 v[76:79], v[144:147], v[208:211], v[76:79]
	v_mfma_f32_16x16x32_bf16 v[120:123], v[148:151], v[174:177], v[120:123]
	v_mfma_f32_16x16x32_bf16 v[116:119], v[156:159], v[174:177], v[116:119]
	v_mfma_f32_16x16x32_bf16 v[104:107], v[148:151], v[188:191], v[104:107]
	v_mfma_f32_16x16x32_bf16 v[100:103], v[156:159], v[188:191], v[100:103]
	v_mfma_f32_16x16x32_bf16 v[88:91], v[148:151], v[196:199], v[88:91]
	v_mfma_f32_16x16x32_bf16 v[84:87], v[156:159], v[196:199], v[84:87]
	v_mfma_f32_16x16x32_bf16 v[72:75], v[148:151], v[204:207], v[72:75]
	v_mfma_f32_16x16x32_bf16 v[68:71], v[156:159], v[204:207], v[68:71]
	v_mfma_f32_16x16x32_bf16 v[120:123], v[152:155], v[178:181], v[120:123]
	v_mfma_f32_16x16x32_bf16 v[116:119], v[170:173], v[178:181], v[116:119]
	v_mfma_f32_16x16x32_bf16 v[104:107], v[152:155], v[192:195], v[104:107]
	v_mfma_f32_16x16x32_bf16 v[100:103], v[170:173], v[192:195], v[100:103]
	v_mfma_f32_16x16x32_bf16 v[88:91], v[152:155], v[200:203], v[88:91]
	v_mfma_f32_16x16x32_bf16 v[84:87], v[170:173], v[200:203], v[84:87]
	v_mfma_f32_16x16x32_bf16 v[72:75], v[152:155], v[208:211], v[72:75]
	v_mfma_f32_16x16x32_bf16 v[68:71], v[170:173], v[208:211], v[68:71]
	s_barrier
	s_add_i32 s22, s67, s30
	v_lshl_add_u64 v[212:213], v[212:213], 0, s[70:71]
	s_mov_b32 m0, s22
	ds_read_b128 v[174:177], v186 offset:49152
	ds_read_b128 v[178:181], v186 offset:50176
	ds_read_b128 v[188:191], v186 offset:51200
	ds_read_b128 v[192:195], v186 offset:52224
	ds_read_b128 v[196:199], v186 offset:53248
	ds_read_b128 v[200:203], v186 offset:54272
	ds_read_b128 v[204:207], v186 offset:55296
	ds_read_b128 v[208:211], v186 offset:56320
	global_load_lds_dwordx4 v[212:213], off
	s_add_i32 m0, s22, 0x2000
	s_add_u32 s22, s26, 0x160080
	v_lshl_add_u64 v[212:213], v[214:215], 0, s[70:71]
	s_addc_u32 s23, s27, 0
	s_add_i32 s26, s69, s30
	global_load_lds_dwordx4 v[212:213], off
	v_lshl_add_u64 v[212:213], s[22:23], 0, v[162:163]
	s_mov_b32 m0, s26
	s_nop 0
	global_load_lds_dwordx4 v[212:213], off
	v_lshl_add_u64 v[212:213], s[22:23], 0, v[0:1]
	s_add_i32 m0, s26, 0x2000
	s_nop 0
	global_load_lds_dwordx4 v[212:213], off
	v_lshl_add_u64 v[212:213], v[216:217], 0, s[70:71]
	s_mov_b32 m0, s38
	s_nop 0
	global_load_lds_dwordx4 v[212:213], off
	v_lshl_add_u64 v[212:213], v[226:227], 0, s[70:71]
	s_mov_b32 m0, s39
	s_nop 0
	global_load_lds_dwordx4 v[212:213], off
	s_waitcnt vmcnt(8)
	s_waitcnt lgkmcnt(0)
	s_barrier
	v_mfma_f32_16x16x32_bf16 v[64:67], v[132:135], v[174:177], v[64:67]
	v_mfma_f32_16x16x32_bf16 v[60:63], v[140:143], v[174:177], v[60:63]
	v_mfma_f32_16x16x32_bf16 v[48:51], v[132:135], v[188:191], v[48:51]
	v_mfma_f32_16x16x32_bf16 v[44:47], v[140:143], v[188:191], v[44:47]
	v_mfma_f32_16x16x32_bf16 v[32:35], v[132:135], v[196:199], v[32:35]
	v_mfma_f32_16x16x32_bf16 v[28:31], v[140:143], v[196:199], v[28:31]
	v_mfma_f32_16x16x32_bf16 v[16:19], v[132:135], v[204:207], v[16:19]
	v_mfma_f32_16x16x32_bf16 v[12:15], v[140:143], v[204:207], v[12:15]
	v_mfma_f32_16x16x32_bf16 v[64:67], v[136:139], v[178:181], v[64:67]
	v_mfma_f32_16x16x32_bf16 v[60:63], v[144:147], v[178:181], v[60:63]
	v_mfma_f32_16x16x32_bf16 v[48:51], v[136:139], v[192:195], v[48:51]
	v_mfma_f32_16x16x32_bf16 v[44:47], v[144:147], v[192:195], v[44:47]
	v_mfma_f32_16x16x32_bf16 v[32:35], v[136:139], v[200:203], v[32:35]
	v_mfma_f32_16x16x32_bf16 v[28:31], v[144:147], v[200:203], v[28:31]
	v_mfma_f32_16x16x32_bf16 v[16:19], v[136:139], v[208:211], v[16:19]
	v_mfma_f32_16x16x32_bf16 v[12:15], v[144:147], v[208:211], v[12:15]
	v_mfma_f32_16x16x32_bf16 v[56:59], v[148:151], v[174:177], v[56:59]
	v_mfma_f32_16x16x32_bf16 v[52:55], v[156:159], v[174:177], v[52:55]
	v_mfma_f32_16x16x32_bf16 v[40:43], v[148:151], v[188:191], v[40:43]
	v_mfma_f32_16x16x32_bf16 v[36:39], v[156:159], v[188:191], v[36:39]
	v_mfma_f32_16x16x32_bf16 v[24:27], v[148:151], v[196:199], v[24:27]
	v_mfma_f32_16x16x32_bf16 v[20:23], v[156:159], v[196:199], v[20:23]
	v_mfma_f32_16x16x32_bf16 v[8:11], v[148:151], v[204:207], v[8:11]
	v_mfma_f32_16x16x32_bf16 v[4:7], v[156:159], v[204:207], v[4:7]
	v_mfma_f32_16x16x32_bf16 v[56:59], v[152:155], v[178:181], v[56:59]
	v_mfma_f32_16x16x32_bf16 v[52:55], v[170:173], v[178:181], v[52:55]
	v_mfma_f32_16x16x32_bf16 v[40:43], v[152:155], v[192:195], v[40:43]
	v_mfma_f32_16x16x32_bf16 v[36:39], v[170:173], v[192:195], v[36:39]
	v_mfma_f32_16x16x32_bf16 v[24:27], v[152:155], v[200:203], v[24:27]
	v_mfma_f32_16x16x32_bf16 v[20:23], v[170:173], v[200:203], v[20:23]
	v_mfma_f32_16x16x32_bf16 v[8:11], v[152:155], v[208:211], v[8:11]
	v_mfma_f32_16x16x32_bf16 v[4:7], v[170:173], v[208:211], v[4:7]
	s_barrier
	s_add_i32 s66, s66, 2
	s_add_u32 s52, s52, 0x100
	s_addc_u32 s54, s54, 0
	s_cmpk_gt_u32 s66, 0x55
	s_mov_b64 s[22:23], s[24:25]
	s_cbranch_scc0 .LBB0_1205
	s_and_b64 vcc, exec, s[18:19]
	s_cbranch_vccz .LBB0_1208
	s_barrier
.LBB0_1208:
	s_setprio 0
	v_lshl_or_b32 v170, s42, 8, v183
	v_lshl_add_u32 v172, s51, 8, v3
	v_ashrrev_i32_e32 v171, 31, v170
	v_lshlrev_b64 v[192:193], 1, v[170:171]
	v_ashrrev_i32_e32 v173, 31, v172
	v_lshl_add_u64 v[174:175], s[12:13], 0, v[192:193]
	v_lshlrev_b64 v[194:195], 12, v[172:173]
	v_lshl_add_u64 v[132:133], v[174:175], 0, v[194:195]
	global_load_dwordx4 v[188:191], v[132:133], off
	global_load_dwordx4 v[156:159], v[132:133], off offset:256
	v_or_b32_e32 v180, 16, v172
	v_ashrrev_i32_e32 v181, 31, v180
	v_lshlrev_b64 v[132:133], 12, v[180:181]
	v_or_b32_e32 v178, 32, v172
	v_lshl_add_u64 v[132:133], v[174:175], 0, v[132:133]
	v_ashrrev_i32_e32 v179, 31, v178
	global_load_dwordx4 v[152:155], v[132:133], off
	global_load_dwordx4 v[148:151], v[132:133], off offset:256
	v_lshlrev_b64 v[132:133], 12, v[178:179]
	v_or_b32_e32 v176, 48, v172
	v_lshl_add_u64 v[132:133], v[174:175], 0, v[132:133]
	v_ashrrev_i32_e32 v177, 31, v176
	global_load_dwordx4 v[144:147], v[132:133], off
	global_load_dwordx4 v[140:143], v[132:133], off offset:256
	v_lshlrev_b64 v[132:133], 12, v[176:177]
	v_lshl_add_u64 v[132:133], v[174:175], 0, v[132:133]
	global_load_dwordx4 v[136:139], v[132:133], off
	s_nop 0
	global_load_dwordx4 v[132:135], v[132:133], off offset:256
	v_lshl_add_u64 v[194:195], s[12:13], 0, v[194:195]
	v_lshl_add_u64 v[192:193], v[194:195], 0, v[192:193]
	s_lshl_b32 s22, s42, 2
	s_ashr_i32 s23, s22, 31
	s_waitcnt vmcnt(0)
	v_lshlrev_b32_e32 v196, 16, v188
	v_and_b32_e32 v197, 0xffff0000, v188
	v_lshlrev_b32_e32 v188, 16, v189
	v_and_b32_e32 v189, 0xffff0000, v189
	v_pk_add_f32 v[130:131], v[130:131], v[188:189]
	v_lshlrev_b32_e32 v188, 16, v190
	v_and_b32_e32 v189, 0xffff0000, v190
	v_pk_add_f32 v[128:129], v[128:129], v[196:197]
	v_lshlrev_b32_e32 v190, 16, v191
	v_and_b32_e32 v191, 0xffff0000, v191
	v_pk_add_f32 v[188:189], v[124:125], v[188:189]
	v_cvt_pk_bf16_f32 v124, v128, v129
	v_cvt_pk_bf16_f32 v125, v130, v131
	v_pk_add_f32 v[190:191], v[126:127], v[190:191]
	v_cvt_pk_bf16_f32 v126, v188, v189
	s_nop 0
	v_cvt_pk_bf16_f32 v127, v190, v191
	global_store_dwordx4 v[192:193], v[124:127], off
	s_nop 1
	v_mul_f32_e32 v124, v129, v129
	v_mul_f32_e32 v125, v131, v131
	v_fmac_f32_e32 v124, v128, v128
	v_fmac_f32_e32 v125, v130, v130
	v_add_f32_e32 v124, v124, v125
	v_mul_f32_e32 v125, v189, v189
	v_mul_f32_e32 v126, v191, v191
	v_fmac_f32_e32 v125, v188, v188
	v_fmac_f32_e32 v126, v190, v190
	v_add_f32_e32 v125, v125, v126
	v_add_f32_e32 v128, v124, v125
	v_lshlrev_b32_e32 v124, 16, v156
	v_and_b32_e32 v125, 0xffff0000, v156
	v_lshlrev_b32_e32 v126, 16, v157
	v_and_b32_e32 v127, 0xffff0000, v157
	v_pk_add_f32 v[120:121], v[120:121], v[124:125]
	v_lshlrev_b32_e32 v124, 16, v158
	v_and_b32_e32 v125, 0xffff0000, v158
	v_pk_add_f32 v[122:123], v[122:123], v[126:127]
	v_lshlrev_b32_e32 v126, 16, v159
	v_and_b32_e32 v127, 0xffff0000, v159
	v_pk_add_f32 v[124:125], v[116:117], v[124:125]
	v_cvt_pk_bf16_f32 v116, v120, v121
	v_cvt_pk_bf16_f32 v117, v122, v123
	v_pk_add_f32 v[126:127], v[118:119], v[126:127]
	v_cvt_pk_bf16_f32 v118, v124, v125
	s_nop 0
	v_cvt_pk_bf16_f32 v119, v126, v127
	global_store_dwordx4 v[192:193], v[116:119], off offset:256
	s_nop 1
	v_mul_f32_e32 v116, v121, v121
	v_mul_f32_e32 v117, v123, v123
	v_fmac_f32_e32 v116, v120, v120
	v_fmac_f32_e32 v117, v122, v122
	v_add_f32_e32 v116, v116, v117
	v_mul_f32_e32 v117, v125, v125
	v_mul_f32_e32 v118, v127, v127
	v_fmac_f32_e32 v117, v124, v124
	v_fmac_f32_e32 v118, v126, v126
	v_add_f32_e32 v117, v117, v118
	v_add_f32_e32 v116, v116, v117
	v_add_f32_e32 v116, v128, v116
	ds_bpermute_b32 v117, v184, v116
	s_waitcnt lgkmcnt(0)
	v_add_f32_e32 v116, v116, v117
	ds_bpermute_b32 v117, v185, v116
	s_and_saveexec_b64 s[24:25], s[4:5]
	s_cbranch_execz .LBB0_1210
	v_lshlrev_b64 v[118:119], 7, v[172:173]
	v_lshl_add_u64 v[118:119], s[16:17], 0, v[118:119]
	v_lshl_add_u64 v[118:119], s[22:23], 2, v[118:119]
	s_lshl_b32 s52, s37, 2
	v_lshl_add_u64 v[118:119], v[118:119], 0, s[52:53]
	s_waitcnt lgkmcnt(0)
	v_add_f32_e32 v116, v116, v117
	global_store_dword v[118:119], v116, off
